# adds: lane^2/^4/^8 exchanges via DPP compositions; P7 pairing guarded by grid==256
# baseline (speedup 1.0000x reference)
; template <int K> __device__ __forceinline__ float shx(float v) { static_assert(K < 32, "use sum32"); return __int_as_float(__builtin_amdgcn_ds_swizzle(__float_as_int(v), (K << 10) | 0x1f)); }
; __device__ __forceinline__ float sum32(float v) { auto rr = __builtin_amdgcn_permlane32_swap(__float_as_uint(v), __float_as_uint(v), false, false); return __uint_as_float(rr[0]) + __uint_as_float(rr[1]); }
; #define GAS __attribute__((address_space(1)))
; __device__ __forceinline__ unsigned pk2(float lo, float hi) { return f2bf(lo) | (f2bf(hi) << 16); }
; __device__ __forceinline__ float wave_sum(float v) { v += shx<1>(v); v += shx<2>(v); v += shx<4>(v); v += shx<8>(v); v += shx<16>(v); return sum32(v); }
; __device__ __forceinline__ void rms_row_to_bf16(const float* xrow, const float* g, bf16* orow, int lane) {
;     const GAS f32x4* xr = (const GAS f32x4*)xrow + lane; const GAS f32x4* gr = (const GAS f32x4*)g + lane;
;     f32x4 v[8]; float s = 0.f;
; #pragma unroll
;     for (int j = 0; j < 8; ++j) { v[j] = __builtin_nontemporal_load(xr + 64 * j); s += (v[j].x * v[j].x + v[j].y * v[j].y) + (v[j].z * v[j].z + v[j].w * v[j].w); }
;     const float rstd = 1.0f / sqrtf(wave_sum(s) * (1.f / DM) + EPS);
;     GAS unsigned long long* o8 = (GAS unsigned long long*)orow + lane;
; #pragma unroll
;     for (int j = 0; j < 8; ++j) { const f32x4 gg = gr[64 * j]; o8[64 * j] = (unsigned long long)pk2(v[j].x * rstd * gg.x, v[j].y * rstd * gg.y) | ((unsigned long long)pk2(v[j].z * rstd * gg.z, v[j].w * rstd * gg.w) << 32); }
.LBB0_108:
	s_cmpk_gt_i32 s6, 0x1fff
	s_mov_b64 s[0:1], -1
	s_cbranch_scc0 .LBB0_110
	s_add_i32 s20, s6, 0xffffe000
	s_lshl_b64 s[0:1], s[20:21], 12
	s_add_u32 s22, s81, s0
	s_addc_u32 s23, s88, s1
	s_lshl_b64 s[0:1], s[20:21], 13
	v_lshl_add_u64 v[2:3], v[56:57], 0, s[0:1]
	global_load_dwordx4 v[62:65], v[2:3], off nt
	global_load_dwordx4 v[66:69], v[2:3], off offset:1024 nt
	global_load_dwordx4 v[22:25], v[2:3], off offset:2048 nt
	global_load_dwordx4 v[18:21], v[2:3], off offset:3072 nt
	v_add_co_u32_e32 v2, vcc, s5, v2
	s_waitcnt vmcnt(3)
	v_mul_f32_e32 v26, v63, v63
	v_addc_co_u32_e32 v3, vcc, 0, v3, vcc
	global_load_dwordx4 v[14:17], v[2:3], off nt
	global_load_dwordx4 v[10:13], v[2:3], off offset:1024 nt
	global_load_dwordx4 v[6:9], v[2:3], off offset:2048 nt
	s_nop 0
	global_load_dwordx4 v[2:5], v[2:3], off offset:3072 nt
	s_nop 0
	global_load_dwordx4 v[70:73], v[30:31], off
	v_mul_f32_e32 v27, v65, v65
	s_waitcnt vmcnt(7)
	v_mul_f32_e32 v28, v67, v67
	v_mul_f32_e32 v29, v69, v69
	s_waitcnt vmcnt(6)
	v_mul_f32_e32 v40, v23, v23
	v_mul_f32_e32 v41, v25, v25
	v_fmac_f32_e32 v26, v62, v62
	v_fmac_f32_e32 v27, v64, v64
	v_fmac_f32_e32 v28, v66, v66
	v_fmac_f32_e32 v29, v68, v68
	s_waitcnt vmcnt(5)
	v_mul_f32_e32 v74, v19, v19
	v_mul_f32_e32 v75, v21, v21
	v_fmac_f32_e32 v40, v22, v22
	v_fmac_f32_e32 v41, v24, v24
	v_add_f32_e32 v26, v26, v27
	v_add_f32_e32 v27, v28, v29
	v_fmac_f32_e32 v74, v18, v18
	v_fmac_f32_e32 v75, v20, v20
	v_add_f32_e32 v28, v40, v41
	v_add_f32_e32 v26, v26, v27
	v_add_f32_e32 v29, v74, v75
	v_add_f32_e32 v26, v26, v28
	v_add_f32_e32 v26, v26, v29
	s_waitcnt vmcnt(4)
	v_mul_f32_e32 v76, v15, v15
	v_mul_f32_e32 v77, v17, v17
	s_waitcnt vmcnt(3)
	v_mul_f32_e32 v78, v11, v11
	v_mul_f32_e32 v79, v13, v13
	v_fmac_f32_e32 v76, v14, v14
	v_fmac_f32_e32 v77, v16, v16
	s_waitcnt vmcnt(2)
	v_mul_f32_e32 v80, v7, v7
	v_mul_f32_e32 v81, v9, v9
	v_fmac_f32_e32 v78, v10, v10
	v_fmac_f32_e32 v79, v12, v12
	v_add_f32_e32 v27, v76, v77
	s_waitcnt vmcnt(1)
	v_mul_f32_e32 v82, v3, v3
	v_mul_f32_e32 v83, v5, v5
	v_fmac_f32_e32 v80, v6, v6
	v_fmac_f32_e32 v81, v8, v8
	v_add_f32_e32 v40, v78, v79
	v_add_f32_e32 v26, v26, v27
	v_fmac_f32_e32 v82, v2, v2
	v_fmac_f32_e32 v83, v4, v4
	v_add_f32_e32 v41, v80, v81
	v_add_f32_e32 v26, v26, v40
	v_add_f32_e32 v74, v82, v83
	v_add_f32_e32 v26, v26, v41
	v_add_f32_e32 v26, v26, v74
	s_nop 1
	v_mov_b32_dpp v27, v26 quad_perm:[1,0,3,2] row_mask:0xf bank_mask:0xf
	s_waitcnt lgkmcnt(0)
	v_add_f32_e32 v26, v26, v27
	s_nop 1
	v_mov_b32_dpp v27, v26 quad_perm:[2,3,0,1] row_mask:0xf bank_mask:0xf
	s_waitcnt lgkmcnt(0)
	v_add_f32_e32 v26, v26, v27
	s_nop 1
	v_mov_b32_dpp v27, v26 quad_perm:[3,2,1,0] row_mask:0xf bank_mask:0xf
	s_nop 1
	v_mov_b32_dpp v27, v27 row_half_mirror row_mask:0xf bank_mask:0xf
	s_waitcnt lgkmcnt(0)
	v_add_f32_e32 v26, v26, v27
	s_nop 1
	v_mov_b32_dpp v27, v26 row_half_mirror row_mask:0xf bank_mask:0xf
	s_nop 1
	v_mov_b32_dpp v27, v27 row_mirror row_mask:0xf bank_mask:0xf
	s_waitcnt lgkmcnt(0)
	v_add_f32_e32 v26, v26, v27
	ds_swizzle_b32 v27, v26 offset:swizzle(SWAP,16)
	s_waitcnt lgkmcnt(0)
	v_add_f32_e32 v26, v26, v27
	v_mov_b32_e32 v27, v26
	s_nop 1
	v_permlane32_swap_b32_e32 v26, v27
	v_add_f32_e32 v26, v26, v27
	v_fmamk_f32 v26, v26, 0x3a000000, v44
	v_mul_f32_e32 v27, 0x4f800000, v26
	v_cmp_gt_f32_e32 vcc, s7, v26
	s_nop 1
	v_cndmask_b32_e32 v26, v26, v27, vcc
	v_sqrt_f32_e32 v27, v26
	s_nop 0
	v_add_u32_e32 v28, -1, v27
	v_add_u32_e32 v29, 1, v27
	v_fma_f32 v40, -v28, v27, v26
	v_fma_f32 v41, -v29, v27, v26
	v_cmp_ge_f32_e64 s[0:1], 0, v40
	s_nop 1
	v_cndmask_b32_e64 v27, v27, v28, s[0:1]
	v_cmp_lt_f32_e64 s[0:1], 0, v41
	s_nop 1
	v_cndmask_b32_e64 v27, v27, v29, s[0:1]
	v_mul_f32_e32 v28, 0x37800000, v27
	v_cndmask_b32_e32 v27, v27, v28, vcc
	v_cmp_class_f32_e32 vcc, v26, v45
	s_nop 1
	v_cndmask_b32_e32 v26, v27, v26, vcc
	v_div_scale_f32 v27, s[0:1], v26, v26, 1.0
	v_rcp_f32_e32 v28, v27
	v_div_scale_f32 v29, vcc, 1.0, v26, 1.0
	s_mov_b64 s[0:1], 0
	v_fma_f32 v40, -v27, v28, 1.0
	v_fmac_f32_e32 v28, v40, v28
	v_mul_f32_e32 v40, v29, v28
	v_fma_f32 v41, -v27, v40, v29
	v_fmac_f32_e32 v40, v41, v28
	v_fma_f32 v27, -v27, v40, v29
	v_div_fmas_f32 v27, v27, v28, v40
	v_div_fixup_f32 v26, v27, v26, 1.0
	v_mul_f32_e32 v27, v62, v26
	v_mul_f32_e32 v29, v64, v26
	v_mul_f32_e32 v28, v63, v26
	v_mul_f32_e32 v40, v65, v26
	s_waitcnt vmcnt(0)
	v_mul_f32_e32 v27, v70, v27
	v_mul_f32_e32 v29, v72, v29
	v_mul_f32_e32 v28, v71, v28
	v_mul_f32_e32 v40, v73, v40
	v_bfe_u32 v41, v27, 16, 1
	v_bfe_u32 v63, v29, 16, 1
	v_bfe_u32 v62, v28, 16, 1
	v_bfe_u32 v64, v40, 16, 1
	v_add3_u32 v27, v27, v41, s26
	v_add3_u32 v29, v29, v63, s26
	v_add3_u32 v28, v28, v62, s26
	v_add3_u32 v40, v40, v64, s26
	v_lshrrev_b32_e32 v27, 16, v27
	v_lshrrev_b32_e32 v29, 16, v29
	v_and_or_b32 v28, v28, s27, v27
	v_and_or_b32 v29, v40, s27, v29
	global_store_dwordx2 v60, v[28:29], s[22:23]
	global_load_dwordx4 v[62:65], v[30:31], off offset:1024
	v_mul_f32_e32 v27, v66, v26
	v_mul_f32_e32 v29, v68, v26
	v_mul_f32_e32 v28, v67, v26
	v_mul_f32_e32 v40, v69, v26
	v_mul_f32_e32 v22, v22, v26
	v_mul_f32_e32 v24, v24, v26
	v_mul_f32_e32 v23, v23, v26
	v_mul_f32_e32 v25, v25, v26
	v_mul_f32_e32 v18, v18, v26
	v_mul_f32_e32 v20, v20, v26
	v_mul_f32_e32 v19, v19, v26
	v_mul_f32_e32 v21, v21, v26
	v_mul_f32_e32 v14, v14, v26
	v_mul_f32_e32 v16, v16, v26
	v_mul_f32_e32 v15, v15, v26
	v_mul_f32_e32 v17, v17, v26
	v_mul_f32_e32 v10, v10, v26
	v_mul_f32_e32 v12, v12, v26
	v_mul_f32_e32 v11, v11, v26
	v_mul_f32_e32 v13, v13, v26
	v_mul_f32_e32 v6, v6, v26
	v_mul_f32_e32 v8, v8, v26
	v_mul_f32_e32 v7, v7, v26
	v_mul_f32_e32 v9, v9, v26
	s_waitcnt vmcnt(0)
; #define GAS __attribute__((address_space(1)))
; __device__ __forceinline__ unsigned pk2(float lo, float hi) { return f2bf(lo) | (f2bf(hi) << 16); }
; __device__ __forceinline__ float wave_sum(float v) { v += shx<1>(v); v += shx<2>(v); v += shx<4>(v); v += shx<8>(v); v += shx<16>(v); return sum32(v); }
; __device__ __forceinline__ void rms_row_to_bf16(const float* xrow, const float* g, bf16* orow, int lane) {
;     const GAS f32x4* xr = (const GAS f32x4*)xrow + lane; const GAS f32x4* gr = (const GAS f32x4*)g + lane;
;     f32x4 v[8]; float s = 0.f;
; #pragma unroll
;     for (int j = 0; j < 8; ++j) { v[j] = __builtin_nontemporal_load(xr + 64 * j); s += (v[j].x * v[j].x + v[j].y * v[j].y) + (v[j].z * v[j].z + v[j].w * v[j].w); }
;     const float rstd = 1.0f / sqrtf(wave_sum(s) * (1.f / DM) + EPS);
;     GAS unsigned long long* o8 = (GAS unsigned long long*)orow + lane;
; #pragma unroll
;     for (int j = 0; j < 8; ++j) { const f32x4 gg = gr[64 * j]; o8[64 * j] = (unsigned long long)pk2(v[j].x * rstd * gg.x, v[j].y * rstd * gg.y) | ((unsigned long long)pk2(v[j].z * rstd * gg.z, v[j].w * rstd * gg.w) << 32); }
; }
; __device__ __forceinline__ void p0_prologue(const Args& a, LAS unsigned char* lds, int wave, int lane, int G) {
;     ...
;     for (int m = gw; m < M + MMEM; m += NGW) {
;         if (m < M) rms_row_to_bf16(a.in[I_X] + (size_t)m * DM, a.in[I_GMIX], (bf16*)(ws + WS_XN) + (size_t)m * DM, lane);
;         else rms_row_to_bf16(a.in[I_MEM] + (size_t)(m - M) * DM, a.in[I_GMEM], (bf16*)(ws + WS_MN) + (size_t)(m - M) * DM, lane);
	v_mul_f32_e32 v27, v62, v27
	v_mul_f32_e32 v29, v64, v29
	v_mul_f32_e32 v28, v63, v28
	v_mul_f32_e32 v40, v65, v40
	v_bfe_u32 v41, v27, 16, 1
	v_bfe_u32 v63, v29, 16, 1
	v_bfe_u32 v62, v28, 16, 1
	v_bfe_u32 v64, v40, 16, 1
	v_add3_u32 v27, v27, v41, s26
	v_add3_u32 v29, v29, v63, s26
	v_add3_u32 v28, v28, v62, s26
	v_add3_u32 v40, v40, v64, s26
	v_lshrrev_b32_e32 v27, 16, v27
	v_lshrrev_b32_e32 v29, 16, v29
	v_and_or_b32 v28, v28, s27, v27
	v_and_or_b32 v29, v40, s27, v29
	global_store_dwordx2 v60, v[28:29], s[22:23] offset:512
	global_load_dwordx4 v[62:65], v[30:31], off offset:2048
	s_waitcnt vmcnt(0)
	v_mul_f32_e32 v22, v62, v22
	v_mul_f32_e32 v24, v64, v24
	v_mul_f32_e32 v23, v63, v23
	v_mul_f32_e32 v25, v65, v25
	v_bfe_u32 v27, v22, 16, 1
	v_bfe_u32 v29, v24, 16, 1
	v_bfe_u32 v28, v23, 16, 1
	v_bfe_u32 v40, v25, 16, 1
	v_add3_u32 v22, v22, v27, s26
	v_add3_u32 v24, v24, v29, s26
	v_add3_u32 v23, v23, v28, s26
	v_add3_u32 v25, v25, v40, s26
	v_lshrrev_b32_e32 v22, 16, v22
	v_lshrrev_b32_e32 v24, 16, v24
	v_and_or_b32 v22, v23, s27, v22
	v_and_or_b32 v23, v25, s27, v24
	global_store_dwordx2 v60, v[22:23], s[22:23] offset:1024
	global_load_dwordx4 v[22:25], v[30:31], off offset:3072
	v_pk_mul_f32 v[2:3], v[2:3], v[26:27] op_sel_hi:[1,0]
	v_mul_f32_e32 v27, v4, v26
	s_waitcnt vmcnt(0)
	v_mul_f32_e32 v18, v18, v22
	v_mul_f32_e32 v20, v20, v24
	v_mul_f32_e32 v19, v19, v23
	v_mul_f32_e32 v21, v21, v25
	v_bfe_u32 v22, v18, 16, 1
	v_bfe_u32 v24, v20, 16, 1
	v_bfe_u32 v23, v19, 16, 1
	v_bfe_u32 v25, v21, 16, 1
	v_add3_u32 v18, v18, v22, s26
	v_add3_u32 v20, v20, v24, s26
	v_add3_u32 v19, v19, v23, s26
	v_add3_u32 v21, v21, v25, s26
	v_lshrrev_b32_e32 v18, 16, v18
	v_lshrrev_b32_e32 v20, 16, v20
	v_and_or_b32 v18, v19, s27, v18
	v_and_or_b32 v19, v21, s27, v20
	global_store_dwordx2 v60, v[18:19], s[22:23] offset:1536
	global_load_dwordx4 v[18:21], v[32:33], off
	s_waitcnt vmcnt(0)
	v_mul_f32_e32 v14, v14, v18
	v_mul_f32_e32 v16, v16, v20
	v_mul_f32_e32 v15, v15, v19
	v_mul_f32_e32 v17, v17, v21
	v_bfe_u32 v18, v14, 16, 1
	v_bfe_u32 v20, v16, 16, 1
	v_bfe_u32 v19, v15, 16, 1
	v_bfe_u32 v21, v17, 16, 1
	v_add3_u32 v14, v14, v18, s26
	v_add3_u32 v16, v16, v20, s26
	v_add3_u32 v15, v15, v19, s26
	v_add3_u32 v17, v17, v21, s26
	v_lshrrev_b32_e32 v14, 16, v14
	v_lshrrev_b32_e32 v16, 16, v16
	v_and_or_b32 v14, v15, s27, v14
	v_and_or_b32 v15, v17, s27, v16
	global_store_dwordx2 v60, v[14:15], s[22:23] offset:2048
	global_load_dwordx4 v[14:17], v[34:35], off
	s_waitcnt vmcnt(0)
	v_mul_f32_e32 v10, v10, v14
	v_mul_f32_e32 v12, v12, v16
	v_mul_f32_e32 v11, v11, v15
	v_mul_f32_e32 v13, v13, v17
	v_bfe_u32 v14, v10, 16, 1
	v_bfe_u32 v16, v12, 16, 1
	v_bfe_u32 v15, v11, 16, 1
	v_bfe_u32 v17, v13, 16, 1
	v_add3_u32 v10, v10, v14, s26
	v_add3_u32 v12, v12, v16, s26
	v_add3_u32 v11, v11, v15, s26
	v_add3_u32 v13, v13, v17, s26
	v_lshrrev_b32_e32 v10, 16, v10
	v_lshrrev_b32_e32 v12, 16, v12
	v_and_or_b32 v10, v11, s27, v10
	v_and_or_b32 v11, v13, s27, v12
	global_store_dwordx2 v60, v[10:11], s[22:23] offset:2560
	global_load_dwordx4 v[10:13], v[36:37], off
	s_waitcnt vmcnt(0)
	v_mul_f32_e32 v6, v6, v10
	v_mul_f32_e32 v8, v8, v12
	v_mul_f32_e32 v7, v7, v11
	v_mul_f32_e32 v9, v9, v13
	v_bfe_u32 v10, v6, 16, 1
	v_bfe_u32 v12, v8, 16, 1
	v_bfe_u32 v11, v7, 16, 1
	v_bfe_u32 v13, v9, 16, 1
	v_add3_u32 v6, v6, v10, s26
	v_add3_u32 v8, v8, v12, s26
	v_add3_u32 v7, v7, v11, s26
	v_add3_u32 v9, v9, v13, s26
	v_lshrrev_b32_e32 v6, 16, v6
	v_lshrrev_b32_e32 v8, 16, v8
	v_and_or_b32 v6, v7, s27, v6
	v_and_or_b32 v7, v9, s27, v8
	global_store_dwordx2 v60, v[6:7], s[22:23] offset:3072
	global_load_dwordx4 v[6:9], v[42:43], off
	s_waitcnt vmcnt(0)
	v_pk_mul_f32 v[2:3], v[2:3], v[6:7]
	s_nop 0
	v_and_b32_sdwa v7, v2, v61 dst_sel:DWORD dst_unused:UNUSED_PAD src0_sel:WORD_1 src1_sel:DWORD
	v_and_b32_sdwa v6, v3, v61 dst_sel:DWORD dst_unused:UNUSED_PAD src0_sel:WORD_1 src1_sel:DWORD
	v_add3_u32 v2, v2, v7, s26
	v_pk_mov_b32 v[4:5], v[4:5], v[8:9] op_sel:[1,0]
	v_add3_u32 v3, v3, v6, s26
	v_lshrrev_b32_e32 v2, 16, v2
	v_pk_mul_f32 v[4:5], v[4:5], v[26:27]
	v_and_or_b32 v2, v3, s27, v2
.LBB0_110:
	s_andn2_b64 vcc, exec, s[0:1]
	s_cbranch_vccnz .LBB0_107
	global_load_dwordx4 v[62:65], v[58:59], off offset:-4096 nt
	global_load_dwordx4 v[26:29], v[58:59], off offset:-3072 nt
	global_load_dwordx4 v[22:25], v[58:59], off offset:-2048 nt
	global_load_dwordx4 v[18:21], v[58:59], off offset:-1024 nt
	global_load_dwordx4 v[14:17], v[58:59], off nt
	global_load_dwordx4 v[10:13], v[58:59], off offset:1024 nt
	global_load_dwordx4 v[6:9], v[58:59], off offset:2048 nt
	global_load_dwordx4 v[2:5], v[58:59], off offset:3072 nt
	global_load_dwordx4 v[66:69], v[46:47], off
	s_add_u32 s22, s16, 0x6900000
	s_addc_u32 s23, s17, 0
	s_waitcnt vmcnt(8)
	v_mul_f32_e32 v40, v63, v63
	v_mul_f32_e32 v41, v65, v65
	s_waitcnt vmcnt(7)
	v_mul_f32_e32 v70, v27, v27
	v_mul_f32_e32 v71, v29, v29
	s_waitcnt vmcnt(6)
	v_mul_f32_e32 v72, v23, v23
	v_mul_f32_e32 v73, v25, v25
	v_fmac_f32_e32 v40, v62, v62
	v_fmac_f32_e32 v41, v64, v64
	v_fmac_f32_e32 v70, v26, v26
	v_fmac_f32_e32 v71, v28, v28
	s_waitcnt vmcnt(5)
	v_mul_f32_e32 v74, v19, v19
	v_mul_f32_e32 v75, v21, v21
	v_fmac_f32_e32 v72, v22, v22
	v_fmac_f32_e32 v73, v24, v24
	v_add_f32_e32 v40, v40, v41
	v_add_f32_e32 v41, v70, v71
	s_waitcnt vmcnt(4)
	v_mul_f32_e32 v76, v15, v15
	v_mul_f32_e32 v77, v17, v17
	v_fmac_f32_e32 v74, v18, v18
	v_fmac_f32_e32 v75, v20, v20
	v_add_f32_e32 v70, v72, v73
	v_add_f32_e32 v40, v40, v41
	s_waitcnt vmcnt(3)
	v_mul_f32_e32 v78, v11, v11
	v_mul_f32_e32 v79, v13, v13
	v_fmac_f32_e32 v76, v14, v14
	v_fmac_f32_e32 v77, v16, v16
	v_add_f32_e32 v71, v74, v75
	v_add_f32_e32 v40, v40, v70
	s_waitcnt vmcnt(2)
; template <int K> __device__ __forceinline__ float shx(float v) { static_assert(K < 32, "use sum32"); return __int_as_float(__builtin_amdgcn_ds_swizzle(__float_as_int(v), (K << 10) | 0x1f)); }
; __device__ __forceinline__ float sum32(float v) { auto rr = __builtin_amdgcn_permlane32_swap(__float_as_uint(v), __float_as_uint(v), false, false); return __uint_as_float(rr[0]) + __uint_as_float(rr[1]); }
; #define GAS __attribute__((address_space(1)))
; __device__ __forceinline__ float wave_sum(float v) { v += shx<1>(v); v += shx<2>(v); v += shx<4>(v); v += shx<8>(v); v += shx<16>(v); return sum32(v); }
; __device__ __forceinline__ void rms_row_to_bf16(const float* xrow, const float* g, bf16* orow, int lane) {
;     const GAS f32x4* xr = (const GAS f32x4*)xrow + lane; const GAS f32x4* gr = (const GAS f32x4*)g + lane;
;     f32x4 v[8]; float s = 0.f;
; #pragma unroll
;     for (int j = 0; j < 8; ++j) { v[j] = __builtin_nontemporal_load(xr + 64 * j); s += (v[j].x * v[j].x + v[j].y * v[j].y) + (v[j].z * v[j].z + v[j].w * v[j].w); }
;     const float rstd = 1.0f / sqrtf(wave_sum(s) * (1.f / DM) + EPS);
	v_mul_f32_e32 v80, v7, v7
	v_mul_f32_e32 v81, v9, v9
	v_fmac_f32_e32 v78, v10, v10
	v_fmac_f32_e32 v79, v12, v12
	v_add_f32_e32 v72, v76, v77
	v_add_f32_e32 v40, v40, v71
	s_waitcnt vmcnt(1)
	v_mul_f32_e32 v82, v3, v3
	v_mul_f32_e32 v83, v5, v5
	v_fmac_f32_e32 v80, v6, v6
	v_fmac_f32_e32 v81, v8, v8
	v_add_f32_e32 v73, v78, v79
	v_add_f32_e32 v40, v40, v72
	v_fmac_f32_e32 v82, v2, v2
	v_fmac_f32_e32 v83, v4, v4
	v_add_f32_e32 v74, v80, v81
	v_add_f32_e32 v40, v40, v73
	v_add_f32_e32 v75, v82, v83
	v_add_f32_e32 v40, v40, v74
	v_add_f32_e32 v40, v40, v75
	s_nop 1
	v_mov_b32_dpp v41, v40 quad_perm:[1,0,3,2] row_mask:0xf bank_mask:0xf
	s_waitcnt lgkmcnt(0)
	v_add_f32_e32 v40, v40, v41
	s_nop 1
	v_mov_b32_dpp v41, v40 quad_perm:[2,3,0,1] row_mask:0xf bank_mask:0xf
	s_waitcnt lgkmcnt(0)
	v_add_f32_e32 v40, v40, v41
	s_nop 1
	v_mov_b32_dpp v41, v40 quad_perm:[3,2,1,0] row_mask:0xf bank_mask:0xf
	s_nop 1
	v_mov_b32_dpp v41, v41 row_half_mirror row_mask:0xf bank_mask:0xf
	s_waitcnt lgkmcnt(0)
	v_add_f32_e32 v40, v40, v41
	s_nop 1
	v_mov_b32_dpp v41, v40 row_half_mirror row_mask:0xf bank_mask:0xf
	s_nop 1
	v_mov_b32_dpp v41, v41 row_mirror row_mask:0xf bank_mask:0xf
	s_waitcnt lgkmcnt(0)
	v_add_f32_e32 v40, v40, v41
	ds_swizzle_b32 v41, v40 offset:swizzle(SWAP,16)
	s_waitcnt lgkmcnt(0)
	v_add_f32_e32 v40, v40, v41
	v_mov_b32_e32 v41, v40
	s_nop 1
	v_permlane32_swap_b32_e32 v40, v41
	v_add_f32_e32 v40, v40, v41
	v_fmamk_f32 v40, v40, 0x3a000000, v44
	v_mul_f32_e32 v41, 0x4f800000, v40
	v_cmp_gt_f32_e32 vcc, s7, v40
	s_nop 1
	v_cndmask_b32_e32 v70, v40, v41, vcc
	v_sqrt_f32_e32 v71, v70
	v_lshl_add_u64 v[40:41], s[16:17], 0, v[38:39]
	v_add_u32_e32 v72, -1, v71
	v_add_u32_e32 v73, 1, v71
	v_fma_f32 v74, -v72, v71, v70
	v_fma_f32 v75, -v73, v71, v70
	v_cmp_ge_f32_e64 s[0:1], 0, v74
	s_nop 1
	v_cndmask_b32_e64 v71, v71, v72, s[0:1]
	v_cmp_lt_f32_e64 s[0:1], 0, v75
	s_nop 1
	v_cndmask_b32_e64 v71, v71, v73, s[0:1]
	v_mul_f32_e32 v72, 0x37800000, v71
	v_cndmask_b32_e32 v71, v71, v72, vcc
	v_cmp_class_f32_e32 vcc, v70, v45
	s_nop 1
	v_cndmask_b32_e32 v72, v71, v70, vcc
	v_div_scale_f32 v73, s[0:1], v72, v72, 1.0
	v_rcp_f32_e32 v74, v73
	v_add_co_u32_e32 v70, vcc, s28, v40
	s_nop 1
	v_addc_co_u32_e32 v71, vcc, 0, v41, vcc
	v_fma_f32 v41, -v73, v74, 1.0
	v_div_scale_f32 v40, vcc, 1.0, v72, 1.0
	v_fmac_f32_e32 v74, v41, v74
	v_mul_f32_e32 v41, v40, v74
	v_fma_f32 v75, -v73, v41, v40
	v_fmac_f32_e32 v41, v75, v74
	v_fma_f32 v40, -v73, v41, v40
	v_div_fmas_f32 v40, v40, v74, v41
	v_div_fixup_f32 v40, v40, v72, 1.0
	v_mul_f32_e32 v41, v62, v40
	v_mul_f32_e32 v62, v63, v40
	v_mul_f32_e32 v63, v64, v40
	v_mul_f32_e32 v64, v65, v40
	s_waitcnt vmcnt(0)
	v_mul_f32_e32 v41, v66, v41
	v_mul_f32_e32 v63, v68, v63
	v_mul_f32_e32 v62, v67, v62
	v_mul_f32_e32 v64, v69, v64
	v_bfe_u32 v65, v41, 16, 1
	v_bfe_u32 v67, v63, 16, 1
	v_bfe_u32 v66, v62, 16, 1
	v_bfe_u32 v68, v64, 16, 1
	v_add3_u32 v41, v41, v65, s26
	v_add3_u32 v63, v63, v67, s26
	v_add3_u32 v62, v62, v66, s26
	v_add3_u32 v64, v64, v68, s26
	v_lshrrev_b32_e32 v41, 16, v41
	v_lshrrev_b32_e32 v63, 16, v63
	v_and_or_b32 v62, v62, s27, v41
	v_and_or_b32 v63, v64, s27, v63
	global_store_dwordx2 v[70:71], v[62:63], off
	global_load_dwordx4 v[62:65], v[46:47], off offset:1024
	v_mul_f32_e32 v26, v26, v40
	v_mul_f32_e32 v28, v28, v40
	v_mul_f32_e32 v27, v27, v40
	v_mul_f32_e32 v29, v29, v40
	v_mul_f32_e32 v22, v22, v40
	v_mul_f32_e32 v24, v24, v40
	v_mul_f32_e32 v23, v23, v40
	v_mul_f32_e32 v25, v25, v40
	v_mul_f32_e32 v18, v18, v40
	v_mul_f32_e32 v20, v20, v40
	v_mul_f32_e32 v19, v19, v40
	v_mul_f32_e32 v21, v21, v40
	v_mul_f32_e32 v14, v14, v40
	v_mul_f32_e32 v16, v16, v40
	v_mul_f32_e32 v15, v15, v40
	v_mul_f32_e32 v17, v17, v40
	v_mul_f32_e32 v10, v10, v40
	v_mul_f32_e32 v12, v12, v40
	v_mul_f32_e32 v11, v11, v40
	v_mul_f32_e32 v13, v13, v40
	v_mul_f32_e32 v6, v6, v40
	v_mul_f32_e32 v8, v8, v40
	v_mul_f32_e32 v7, v7, v40
	v_mul_f32_e32 v9, v9, v40
	s_waitcnt vmcnt(0)
; #define GAS __attribute__((address_space(1)))
; __device__ __forceinline__ unsigned pk2(float lo, float hi) { return f2bf(lo) | (f2bf(hi) << 16); }
; __device__ __forceinline__ void rms_row_to_bf16(const float* xrow, const float* g, bf16* orow, int lane) {
;     ...
;     GAS unsigned long long* o8 = (GAS unsigned long long*)orow + lane;
; #pragma unroll
;     for (int j = 0; j < 8; ++j) { const f32x4 gg = gr[64 * j]; o8[64 * j] = (unsigned long long)pk2(v[j].x * rstd * gg.x, v[j].y * rstd * gg.y) | ((unsigned long long)pk2(v[j].z * rstd * gg.z, v[j].w * rstd * gg.w) << 32); }
	v_mul_f32_e32 v26, v62, v26
	v_mul_f32_e32 v28, v64, v28
	v_mul_f32_e32 v27, v63, v27
	v_mul_f32_e32 v29, v65, v29
	v_bfe_u32 v41, v26, 16, 1
	v_bfe_u32 v63, v28, 16, 1
	v_bfe_u32 v62, v27, 16, 1
	v_bfe_u32 v64, v29, 16, 1
	v_add3_u32 v26, v26, v41, s26
	v_add3_u32 v28, v28, v63, s26
	v_add3_u32 v27, v27, v62, s26
	v_add3_u32 v29, v29, v64, s26
	v_lshrrev_b32_e32 v26, 16, v26
	v_lshrrev_b32_e32 v28, 16, v28
	v_and_or_b32 v26, v27, s27, v26
	v_and_or_b32 v27, v29, s27, v28
	global_store_dwordx2 v[70:71], v[26:27], off offset:512
	global_load_dwordx4 v[26:29], v[46:47], off offset:2048
	v_pk_mul_f32 v[2:3], v[2:3], v[40:41] op_sel_hi:[1,0]
	v_mul_f32_e32 v41, v4, v40
	s_waitcnt vmcnt(0)
	v_mul_f32_e32 v22, v26, v22
	v_mul_f32_e32 v24, v28, v24
	v_mul_f32_e32 v23, v27, v23
	v_mul_f32_e32 v25, v29, v25
	v_bfe_u32 v26, v22, 16, 1
	v_bfe_u32 v28, v24, 16, 1
	v_bfe_u32 v27, v23, 16, 1
	v_bfe_u32 v29, v25, 16, 1
	v_add3_u32 v22, v22, v26, s26
	v_add3_u32 v24, v24, v28, s26
	v_add3_u32 v23, v23, v27, s26
	v_add3_u32 v25, v25, v29, s26
	v_lshrrev_b32_e32 v22, 16, v22
	v_lshrrev_b32_e32 v24, 16, v24
	v_and_or_b32 v22, v23, s27, v22
	v_and_or_b32 v23, v25, s27, v24
	global_store_dwordx2 v[70:71], v[22:23], off offset:1024
	global_load_dwordx4 v[22:25], v[46:47], off offset:3072
	s_waitcnt vmcnt(0)
	v_mul_f32_e32 v18, v18, v22
	v_mul_f32_e32 v20, v20, v24
	v_mul_f32_e32 v19, v19, v23
	v_mul_f32_e32 v21, v21, v25
	v_bfe_u32 v22, v18, 16, 1
	v_bfe_u32 v24, v20, 16, 1
	v_bfe_u32 v23, v19, 16, 1
	v_bfe_u32 v25, v21, 16, 1
	v_add3_u32 v18, v18, v22, s26
	v_add3_u32 v20, v20, v24, s26
	v_add3_u32 v19, v19, v23, s26
	v_add3_u32 v21, v21, v25, s26
	v_lshrrev_b32_e32 v18, 16, v18
	v_lshrrev_b32_e32 v20, 16, v20
	v_and_or_b32 v18, v19, s27, v18
	v_and_or_b32 v19, v21, s27, v20
	global_store_dwordx2 v[70:71], v[18:19], off offset:1536
	global_load_dwordx4 v[18:21], v[48:49], off
	s_waitcnt vmcnt(0)
	v_mul_f32_e32 v14, v14, v18
	v_mul_f32_e32 v16, v16, v20
	v_mul_f32_e32 v15, v15, v19
	v_mul_f32_e32 v17, v17, v21
	v_bfe_u32 v18, v14, 16, 1
	v_bfe_u32 v20, v16, 16, 1
	v_bfe_u32 v19, v15, 16, 1
	v_bfe_u32 v21, v17, 16, 1
	v_add3_u32 v14, v14, v18, s26
	v_add3_u32 v16, v16, v20, s26
	v_add3_u32 v15, v15, v19, s26
	v_add3_u32 v17, v17, v21, s26
	v_lshrrev_b32_e32 v14, 16, v14
	v_lshrrev_b32_e32 v16, 16, v16
	v_and_or_b32 v14, v15, s27, v14
	v_and_or_b32 v15, v17, s27, v16
	global_store_dwordx2 v[70:71], v[14:15], off offset:2048
	global_load_dwordx4 v[14:17], v[50:51], off
	s_waitcnt vmcnt(0)
	v_mul_f32_e32 v10, v10, v14
	v_mul_f32_e32 v12, v12, v16
	v_mul_f32_e32 v11, v11, v15
	v_mul_f32_e32 v13, v13, v17
	v_bfe_u32 v14, v10, 16, 1
	v_bfe_u32 v16, v12, 16, 1
	v_bfe_u32 v15, v11, 16, 1
	v_bfe_u32 v17, v13, 16, 1
	v_add3_u32 v10, v10, v14, s26
	v_add3_u32 v12, v12, v16, s26
	v_add3_u32 v11, v11, v15, s26
	v_add3_u32 v13, v13, v17, s26
	v_lshrrev_b32_e32 v10, 16, v10
	v_lshrrev_b32_e32 v12, 16, v12
	v_and_or_b32 v10, v11, s27, v10
	v_and_or_b32 v11, v13, s27, v12
	global_store_dwordx2 v[70:71], v[10:11], off offset:2560
	global_load_dwordx4 v[10:13], v[52:53], off
	s_waitcnt vmcnt(0)
	v_mul_f32_e32 v6, v6, v10
	v_mul_f32_e32 v8, v8, v12
	v_mul_f32_e32 v7, v7, v11
	v_mul_f32_e32 v9, v9, v13
	v_bfe_u32 v10, v6, 16, 1
	v_bfe_u32 v12, v8, 16, 1
	v_bfe_u32 v11, v7, 16, 1
	v_bfe_u32 v13, v9, 16, 1
	v_add3_u32 v6, v6, v10, s26
	v_add3_u32 v8, v8, v12, s26
	v_add3_u32 v7, v7, v11, s26
	v_add3_u32 v9, v9, v13, s26
	v_lshrrev_b32_e32 v6, 16, v6
	v_lshrrev_b32_e32 v8, 16, v8
	v_and_or_b32 v6, v7, s27, v6
	v_and_or_b32 v7, v9, s27, v8
	global_store_dwordx2 v[70:71], v[6:7], off offset:3072
	global_load_dwordx4 v[6:9], v[54:55], off
	s_waitcnt vmcnt(0)
	v_pk_mul_f32 v[2:3], v[2:3], v[6:7]
	s_nop 0
	v_and_b32_sdwa v7, v2, v61 dst_sel:DWORD dst_unused:UNUSED_PAD src0_sel:WORD_1 src1_sel:DWORD
	v_and_b32_sdwa v6, v3, v61 dst_sel:DWORD dst_unused:UNUSED_PAD src0_sel:WORD_1 src1_sel:DWORD
	v_add3_u32 v2, v2, v7, s26
	v_pk_mov_b32 v[4:5], v[4:5], v[8:9] op_sel:[1,0]
	v_add3_u32 v3, v3, v6, s26
	v_lshrrev_b32_e32 v2, 16, v2
	v_and_or_b32 v2, v3, s27, v2
	v_pk_mul_f32 v[4:5], v[4:5], v[40:41]
	s_branch .LBB0_107

; template <int K> __device__ __forceinline__ float shx(float v) { static_assert(K < 32, "use sum32"); return __int_as_float(__builtin_amdgcn_ds_swizzle(__float_as_int(v), (K << 10) | 0x1f)); }
; __device__ __forceinline__ unsigned pk2(float lo, float hi) { return f2bf(lo) | (f2bf(hi) << 16); }
; __device__ __forceinline__ float bflo(unsigned w) { return __uint_as_float(w << 16); }
; __device__ __forceinline__ float bfhi(unsigned w) { return __uint_as_float(w & 0xffff0000u); }
; __global__ void __launch_bounds__(NTHR, LB2) hymba_fwd(Args a) {
;     ...
;       for (int L = P2B_FIRST; L < 256; L += P2B_STRIDE) { const int pm = L >> 3, nblk = L & 7, j = pm & 7, c8 = nblk * 128 + (tid & 15) * 8;
;         f32x4 hi0 = {0.f, 0.f, 0.f, 0.f}, hi1 = {0.f, 0.f, 0.f, 0.f};
;         for (int i = 0; i < j; ++i) { const float* eh = ENDH + (pm - j + i) * 1024 + c8; const float* ea = ENDA + (pm - j + i) * 1024 + c8;
;             hi0 = *(const f32x4*)ea * hi0 + *(const f32x4*)eh; hi1 = *(const f32x4*)(ea + 4) * hi1 + *(const f32x4*)(eh + 4); }
; #pragma unroll 2
;         for (int p = 0; p < 8; ++p) { const unsigned row = (unsigned)(pm * 256 + p * 32 + (tid >> 4)), o = (row * 1024u + c8) * 2u;
;             const v4u hw = __builtin_nontemporal_load((const v4u*)((const char*)HL + o)), aw = __builtin_nontemporal_load((const v4u*)((const char*)AC + o)), gw = __builtin_nontemporal_load((const v4u*)((const char*)GG + o));
;             const f32x4 y0 = ((f32x4){bflo(hw.x), bfhi(hw.x), bflo(hw.y), bfhi(hw.y)} + (f32x4){bflo(aw.x), bfhi(aw.x), bflo(aw.y), bfhi(aw.y)} * hi0) * (f32x4){bflo(gw.x), bfhi(gw.x), bflo(gw.y), bfhi(gw.y)};
;             const f32x4 y1 = ((f32x4){bflo(hw.z), bfhi(hw.z), bflo(hw.w), bfhi(hw.w)} + (f32x4){bflo(aw.z), bfhi(aw.z), bflo(aw.w), bfhi(aw.w)} * hi1) * (f32x4){bflo(gw.z), bfhi(gw.z), bflo(gw.w), bfhi(gw.w)};
;             float ss = (y0.x * y0.x + y0.y * y0.y) + (y0.z * y0.z + y0.w * y0.w) + (y1.x * y1.x + y1.y * y1.y) + (y1.z * y1.z + y1.w * y1.w);
;             v4u ow; ow.x = pk2(y0.x, y0.y); ow.y = pk2(y0.z, y0.w); ow.z = pk2(y1.x, y1.y); ow.w = pk2(y1.z, y1.w);
;             *(v4u*)((char*)MIX + ((size_t)row * 2048 + 1024 + c8) * 2) = ow;
;             ss += shx<1>(ss); ss += shx<2>(ss); ss += shx<4>(ss); ss += shx<8>(ss);
;             if ((tid & 15) == 0) SSQL[row * 8 + nblk] = ss; } } }
.LBB0_796:
	s_waitcnt lgkmcnt(0)
	global_load_dwordx4 v[0:3], v26, s[26:27] nt
	global_load_dwordx4 v[28:31], v26, s[28:29] nt
	global_load_dwordx4 v[32:35], v26, s[20:21] nt
	v_subrev_u32_e32 v4, 32, v18
	s_mov_b32 s12, 0xf000000
	s_waitcnt vmcnt(2)
	v_lshlrev_b32_e32 v20, 16, v0
	v_and_b32_e32 v21, 0xffff0000, v0
	v_lshlrev_b32_e32 v0, 16, v1
	v_and_b32_e32 v1, 0xffff0000, v1
	s_waitcnt vmcnt(1)
	v_lshlrev_b32_e32 v36, 16, v28
	v_and_b32_e32 v37, 0xffff0000, v28
	v_lshlrev_b32_e32 v28, 16, v29
	v_and_b32_e32 v29, 0xffff0000, v29
	v_pk_fma_f32 v[20:21], v[10:11], v[36:37], v[20:21]
	v_pk_fma_f32 v[0:1], v[12:13], v[28:29], v[0:1]
	s_waitcnt vmcnt(0)
	v_lshlrev_b32_e32 v28, 16, v32
	v_and_b32_e32 v29, 0xffff0000, v32
	v_lshlrev_b32_e32 v32, 16, v33
	v_and_b32_e32 v33, 0xffff0000, v33
	v_pk_mul_f32 v[0:1], v[0:1], v[32:33]
	v_pk_mul_f32 v[20:21], v[20:21], v[28:29]
	v_lshlrev_b32_e32 v28, 16, v2
	v_and_b32_e32 v29, 0xffff0000, v2
	v_lshlrev_b32_e32 v2, 16, v3
	v_and_b32_e32 v3, 0xffff0000, v3
	v_lshlrev_b32_e32 v32, 16, v30
	v_and_b32_e32 v33, 0xffff0000, v30
	v_lshlrev_b32_e32 v30, 16, v31
	v_and_b32_e32 v31, 0xffff0000, v31
	v_pk_fma_f32 v[28:29], v[14:15], v[32:33], v[28:29]
	v_pk_fma_f32 v[2:3], v[16:17], v[30:31], v[2:3]
	v_lshlrev_b32_e32 v30, 16, v34
	v_and_b32_e32 v31, 0xffff0000, v34
	v_mul_f32_e32 v19, v21, v21
	v_mul_f32_e32 v27, v1, v1
	v_pk_mul_f32 v[28:29], v[28:29], v[30:31]
	v_fmac_f32_e32 v19, v20, v20
	v_fmac_f32_e32 v27, v0, v0
	v_lshlrev_b32_e32 v32, 16, v35
	v_and_b32_e32 v33, 0xffff0000, v35
	v_add_f32_e32 v19, v19, v27
	v_mul_f32_e32 v27, v29, v29
	v_pk_mul_f32 v[2:3], v[2:3], v[32:33]
	v_fmac_f32_e32 v27, v28, v28
	v_add_f32_e32 v19, v27, v19
	v_mul_f32_e32 v27, v3, v3
	v_fmac_f32_e32 v27, v2, v2
	v_add_f32_e32 v19, v27, v19
	v_and_b32_sdwa v27, v0, v25 dst_sel:DWORD dst_unused:UNUSED_PAD src0_sel:WORD_1 src1_sel:DWORD
	v_and_b32_sdwa v30, v20, v25 dst_sel:DWORD dst_unused:UNUSED_PAD src0_sel:WORD_1 src1_sel:DWORD
	v_add3_u32 v20, v20, v30, s7
	v_add3_u32 v0, v0, v27, s7
	v_and_b32_sdwa v27, v1, v25 dst_sel:DWORD dst_unused:UNUSED_PAD src0_sel:WORD_1 src1_sel:DWORD
	v_and_b32_sdwa v30, v21, v25 dst_sel:DWORD dst_unused:UNUSED_PAD src0_sel:WORD_1 src1_sel:DWORD
	v_add3_u32 v1, v1, v27, s7
	v_add3_u32 v21, v21, v30, s7
	v_and_b32_e32 v1, 0xffff0000, v1
	v_and_b32_e32 v21, 0xffff0000, v21
	v_or_b32_sdwa v1, v1, v0 dst_sel:DWORD dst_unused:UNUSED_PAD src0_sel:DWORD src1_sel:WORD_1
	v_or_b32_sdwa v0, v21, v20 dst_sel:DWORD dst_unused:UNUSED_PAD src0_sel:DWORD src1_sel:WORD_1
	v_and_b32_sdwa v20, v2, v25 dst_sel:DWORD dst_unused:UNUSED_PAD src0_sel:WORD_1 src1_sel:DWORD
	v_add3_u32 v2, v2, v20, s7
	v_and_b32_sdwa v20, v3, v25 dst_sel:DWORD dst_unused:UNUSED_PAD src0_sel:WORD_1 src1_sel:DWORD
	v_and_b32_sdwa v27, v29, v25 dst_sel:DWORD dst_unused:UNUSED_PAD src0_sel:WORD_1 src1_sel:DWORD
	v_and_b32_sdwa v21, v28, v25 dst_sel:DWORD dst_unused:UNUSED_PAD src0_sel:WORD_1 src1_sel:DWORD
	v_add3_u32 v3, v3, v20, s7
	v_add3_u32 v20, v29, v27, s7
	v_add3_u32 v21, v28, v21, s7
	v_and_b32_e32 v3, 0xffff0000, v3
	v_and_b32_e32 v20, 0xffff0000, v20
	v_or_b32_sdwa v3, v3, v2 dst_sel:DWORD dst_unused:UNUSED_PAD src0_sel:DWORD src1_sel:WORD_1
	v_or_b32_sdwa v2, v20, v21 dst_sel:DWORD dst_unused:UNUSED_PAD src0_sel:DWORD src1_sel:WORD_1
	v_lshlrev_b64 v[20:21], 12, v[4:5]
	v_lshl_add_u64 v[20:21], v[6:7], 0, v[20:21]
	v_add_co_u32_e32 v20, vcc, s12, v20
	v_add_u32_e32 v4, s0, v22
	s_nop 0
	v_addc_co_u32_e32 v21, vcc, 0, v21, vcc
	global_store_dwordx4 v[20:21], v[0:3], off offset:2048
	s_nop 1
	v_mov_b32_dpp v0, v19 quad_perm:[1,0,3,2] row_mask:0xf bank_mask:0xf
	s_waitcnt lgkmcnt(0)
	v_add_f32_e32 v0, v19, v0
	s_nop 1
	v_mov_b32_dpp v1, v0 quad_perm:[2,3,0,1] row_mask:0xf bank_mask:0xf
	s_waitcnt lgkmcnt(0)
	v_add_f32_e32 v0, v0, v1
	s_nop 1
	v_mov_b32_dpp v1, v0 quad_perm:[3,2,1,0] row_mask:0xf bank_mask:0xf
	s_nop 1
	v_mov_b32_dpp v1, v1 row_half_mirror row_mask:0xf bank_mask:0xf
	s_waitcnt lgkmcnt(0)
	v_add_f32_e32 v0, v0, v1
	s_nop 1
	v_mov_b32_dpp v1, v0 row_half_mirror row_mask:0xf bank_mask:0xf
	s_nop 1
	v_mov_b32_dpp v1, v1 row_mirror row_mask:0xf bank_mask:0xf
	s_and_saveexec_b64 s[12:13], s[34:35]
	s_cbranch_execz .LBB0_798
	v_lshl_add_u64 v[2:3], v[4:5], 2, s[24:25]
	s_waitcnt lgkmcnt(0)
	v_add_f32_e32 v0, v0, v1
	global_store_dword v[2:3], v0, off
; template <int K> __device__ __forceinline__ float shx(float v) { static_assert(K < 32, "use sum32"); return __int_as_float(__builtin_amdgcn_ds_swizzle(__float_as_int(v), (K << 10) | 0x1f)); }
; __device__ __forceinline__ unsigned pk2(float lo, float hi) { return f2bf(lo) | (f2bf(hi) << 16); }
; __device__ __forceinline__ float bflo(unsigned w) { return __uint_as_float(w << 16); }
; __device__ __forceinline__ float bfhi(unsigned w) { return __uint_as_float(w & 0xffff0000u); }
; __global__ void __launch_bounds__(NTHR, LB2) hymba_fwd(Args a) {
;     ...
; #pragma unroll 2
;         for (int p = 0; p < 8; ++p) { const unsigned row = (unsigned)(pm * 256 + p * 32 + (tid >> 4)), o = (row * 1024u + c8) * 2u;
;             const v4u hw = __builtin_nontemporal_load((const v4u*)((const char*)HL + o)), aw = __builtin_nontemporal_load((const v4u*)((const char*)AC + o)), gw = __builtin_nontemporal_load((const v4u*)((const char*)GG + o));
;             const f32x4 y0 = ((f32x4){bflo(hw.x), bfhi(hw.x), bflo(hw.y), bfhi(hw.y)} + (f32x4){bflo(aw.x), bfhi(aw.x), bflo(aw.y), bfhi(aw.y)} * hi0) * (f32x4){bflo(gw.x), bfhi(gw.x), bflo(gw.y), bfhi(gw.y)};
;             const f32x4 y1 = ((f32x4){bflo(hw.z), bfhi(hw.z), bflo(hw.w), bfhi(hw.w)} + (f32x4){bflo(aw.z), bfhi(aw.z), bflo(aw.w), bfhi(aw.w)} * hi1) * (f32x4){bflo(gw.z), bfhi(gw.z), bflo(gw.w), bfhi(gw.w)};
;             float ss = (y0.x * y0.x + y0.y * y0.y) + (y0.z * y0.z + y0.w * y0.w) + (y1.x * y1.x + y1.y * y1.y) + (y1.z * y1.z + y1.w * y1.w);
;             v4u ow; ow.x = pk2(y0.x, y0.y); ow.y = pk2(y0.z, y0.w); ow.z = pk2(y1.x, y1.y); ow.w = pk2(y1.z, y1.w);
;             *(v4u*)((char*)MIX + ((size_t)row * 2048 + 1024 + c8) * 2) = ow;
;             ss += shx<1>(ss); ss += shx<2>(ss); ss += shx<4>(ss); ss += shx<8>(ss);
;             if ((tid & 15) == 0) SSQL[row * 8 + nblk] = ss; } } }
.LBB0_798:
	s_or_b64 exec, exec, s[12:13]
	v_add_u32_e32 v19, 0x10000, v26
	s_waitcnt lgkmcnt(0)
	global_load_dwordx4 v[0:3], v19, s[26:27] nt
	global_load_dwordx4 v[28:31], v19, s[28:29] nt
	global_load_dwordx4 v[32:35], v19, s[20:21] nt
	s_waitcnt vmcnt(2)
	v_lshlrev_b32_e32 v20, 16, v0
	v_and_b32_e32 v21, 0xffff0000, v0
	v_lshlrev_b32_e32 v0, 16, v1
	v_and_b32_e32 v1, 0xffff0000, v1
	s_waitcnt vmcnt(1)
	v_lshlrev_b32_e32 v36, 16, v28
	v_and_b32_e32 v37, 0xffff0000, v28
	v_lshlrev_b32_e32 v28, 16, v29
	v_and_b32_e32 v29, 0xffff0000, v29
	v_pk_fma_f32 v[20:21], v[10:11], v[36:37], v[20:21]
	v_pk_fma_f32 v[0:1], v[12:13], v[28:29], v[0:1]
	s_waitcnt vmcnt(0)
	v_lshlrev_b32_e32 v28, 16, v32
	v_and_b32_e32 v29, 0xffff0000, v32
	v_lshlrev_b32_e32 v32, 16, v33
	v_and_b32_e32 v33, 0xffff0000, v33
	v_pk_mul_f32 v[0:1], v[0:1], v[32:33]
	v_pk_mul_f32 v[20:21], v[20:21], v[28:29]
	v_lshlrev_b32_e32 v28, 16, v2
	v_and_b32_e32 v29, 0xffff0000, v2
	v_lshlrev_b32_e32 v2, 16, v3
	v_and_b32_e32 v3, 0xffff0000, v3
	v_lshlrev_b32_e32 v32, 16, v30
	v_and_b32_e32 v33, 0xffff0000, v30
	v_lshlrev_b32_e32 v30, 16, v31
	v_and_b32_e32 v31, 0xffff0000, v31
	v_pk_fma_f32 v[28:29], v[14:15], v[32:33], v[28:29]
	v_pk_fma_f32 v[2:3], v[16:17], v[30:31], v[2:3]
	v_lshlrev_b32_e32 v30, 16, v34
	v_and_b32_e32 v31, 0xffff0000, v34
	v_mul_f32_e32 v19, v21, v21
	v_mul_f32_e32 v27, v1, v1
	v_pk_mul_f32 v[28:29], v[28:29], v[30:31]
	v_fmac_f32_e32 v19, v20, v20
	v_fmac_f32_e32 v27, v0, v0
	v_lshlrev_b32_e32 v32, 16, v35
	v_and_b32_e32 v33, 0xffff0000, v35
	v_add_f32_e32 v19, v19, v27
	v_mul_f32_e32 v27, v29, v29
	v_pk_mul_f32 v[2:3], v[2:3], v[32:33]
	v_fmac_f32_e32 v27, v28, v28
	v_add_f32_e32 v19, v27, v19
	v_mul_f32_e32 v27, v3, v3
	v_fmac_f32_e32 v27, v2, v2
	v_add_f32_e32 v27, v27, v19
	v_and_b32_sdwa v19, v0, v25 dst_sel:DWORD dst_unused:UNUSED_PAD src0_sel:WORD_1 src1_sel:DWORD
	v_and_b32_sdwa v30, v20, v25 dst_sel:DWORD dst_unused:UNUSED_PAD src0_sel:WORD_1 src1_sel:DWORD
	v_add3_u32 v20, v20, v30, s7
	v_add3_u32 v0, v0, v19, s7
	v_and_b32_sdwa v19, v1, v25 dst_sel:DWORD dst_unused:UNUSED_PAD src0_sel:WORD_1 src1_sel:DWORD
	v_and_b32_sdwa v30, v21, v25 dst_sel:DWORD dst_unused:UNUSED_PAD src0_sel:WORD_1 src1_sel:DWORD
	v_add3_u32 v1, v1, v19, s7
	v_add3_u32 v19, v21, v30, s7
	v_and_b32_e32 v1, 0xffff0000, v1
	v_and_b32_e32 v19, 0xffff0000, v19
	v_or_b32_sdwa v1, v1, v0 dst_sel:DWORD dst_unused:UNUSED_PAD src0_sel:DWORD src1_sel:WORD_1
	v_or_b32_sdwa v0, v19, v20 dst_sel:DWORD dst_unused:UNUSED_PAD src0_sel:DWORD src1_sel:WORD_1
	v_and_b32_sdwa v19, v2, v25 dst_sel:DWORD dst_unused:UNUSED_PAD src0_sel:WORD_1 src1_sel:DWORD
	v_add3_u32 v2, v2, v19, s7
	v_and_b32_sdwa v19, v3, v25 dst_sel:DWORD dst_unused:UNUSED_PAD src0_sel:WORD_1 src1_sel:DWORD
	v_and_b32_sdwa v21, v29, v25 dst_sel:DWORD dst_unused:UNUSED_PAD src0_sel:WORD_1 src1_sel:DWORD
	v_and_b32_sdwa v20, v28, v25 dst_sel:DWORD dst_unused:UNUSED_PAD src0_sel:WORD_1 src1_sel:DWORD
	v_add3_u32 v3, v3, v19, s7
	v_add3_u32 v19, v29, v21, s7
	v_add3_u32 v20, v28, v20, s7
	v_and_b32_e32 v3, 0xffff0000, v3
	v_and_b32_e32 v19, 0xffff0000, v19
	v_or_b32_sdwa v3, v3, v2 dst_sel:DWORD dst_unused:UNUSED_PAD src0_sel:DWORD src1_sel:WORD_1
	v_or_b32_sdwa v2, v19, v20 dst_sel:DWORD dst_unused:UNUSED_PAD src0_sel:DWORD src1_sel:WORD_1
	v_mov_b32_e32 v19, v5
	v_lshlrev_b64 v[20:21], 12, v[18:19]
	v_lshl_add_u64 v[20:21], v[6:7], 0, v[20:21]
	v_add_co_u32_e32 v20, vcc, 0xf000000, v20
	s_nop 1
	v_addc_co_u32_e32 v21, vcc, 0, v21, vcc
	global_store_dwordx4 v[20:21], v[0:3], off offset:2048
	s_nop 1
	v_mov_b32_dpp v0, v27 quad_perm:[1,0,3,2] row_mask:0xf bank_mask:0xf
	s_waitcnt lgkmcnt(0)
	v_add_f32_e32 v0, v27, v0
	s_nop 1
	v_mov_b32_dpp v1, v0 quad_perm:[2,3,0,1] row_mask:0xf bank_mask:0xf
	s_waitcnt lgkmcnt(0)
	v_add_f32_e32 v0, v0, v1
	s_nop 1
	v_mov_b32_dpp v1, v0 quad_perm:[3,2,1,0] row_mask:0xf bank_mask:0xf
	s_nop 1
	v_mov_b32_dpp v1, v1 row_half_mirror row_mask:0xf bank_mask:0xf
	s_waitcnt lgkmcnt(0)
	v_add_f32_e32 v0, v0, v1
	s_nop 1
	v_mov_b32_dpp v1, v0 row_half_mirror row_mask:0xf bank_mask:0xf
	s_nop 1
	v_mov_b32_dpp v1, v1 row_mirror row_mask:0xf bank_mask:0xf
	s_and_saveexec_b64 s[12:13], s[34:35]
	s_cbranch_execz .LBB0_795
	v_add_u32_e32 v4, 0x100, v4
	v_lshl_add_u64 v[2:3], v[4:5], 2, s[24:25]
	s_waitcnt lgkmcnt(0)
	v_add_f32_e32 v0, v0, v1
	global_store_dword v[2:3], v0, off
	s_branch .LBB0_795

; template <int K> __device__ __forceinline__ float shx(float v) { static_assert(K < 32, "use sum32"); return __int_as_float(__builtin_amdgcn_ds_swizzle(__float_as_int(v), (K << 10) | 0x1f)); }
; template <class TIn, class TOut, int ost, bool HAS_SS>
; __device__ __forceinline__ void causal_swa_block(const BlockRef<TIn, TOut>& cur_, const BlockRef<TIn, TOut>& nxt_, int skv, int W, char* lds, Seam<TIn>& S, int cbl  ) {
;     ...
;     for (int r = 0; r < 16; ++r) { const unsigned rowoff = ob0 + (unsigned)(((r & 3) + 8 * (r >> 2)) * ost * 2); float ss_ = 0.f;
; #pragma unroll
;         for (int d0 = 0; d0 < 4; ++d0) { const float v = o[d0][r] * rli[r]; ss_ += v * v;
;             const float vn = shx<1>(v);
;             if ((r32e & 1) == 0) *(unsigned*)(Ob + rowoff + d0 * 64) = cvtpk(v, vn); }
;         if (HAS_SS) { ss_ += shx<1>(ss_); ss_ += shx<2>(ss_); ss_ += shx<4>(ss_); ss_ += shx<8>(ss_); ss_ += shx<16>(ss_);
;             if (r32e == 0) *(float*)((char*)cur.SS + (unsigned)(wid * QBLK + 4 * hie + (r & 3) + 8 * (r >> 2)) * 32u) = ss_; }
.LBB0_932:
	s_or_b64 exec, exec, s[12:13]
	v_mul_f32_e32 v14, v48, v48
	v_fmac_f32_e32 v14, v0, v0
	v_fmac_f32_e32 v14, v32, v32
	v_fmac_f32_e32 v14, v16, v16
	s_nop 1
	v_mov_b32_dpp v0, v14 quad_perm:[1,0,3,2] row_mask:0xf bank_mask:0xf
	v_cmp_eq_u32_e64 s[34:35], 0, v198
	s_waitcnt lgkmcnt(0)
	v_add_f32_e32 v0, v14, v0
	s_nop 1
	v_mov_b32_dpp v14, v0 quad_perm:[2,3,0,1] row_mask:0xf bank_mask:0xf
	s_waitcnt lgkmcnt(0)
	v_add_f32_e32 v0, v0, v14
	s_nop 1
	v_mov_b32_dpp v14, v0 quad_perm:[3,2,1,0] row_mask:0xf bank_mask:0xf
	s_nop 1
	v_mov_b32_dpp v14, v14 row_half_mirror row_mask:0xf bank_mask:0xf
	s_waitcnt lgkmcnt(0)
	v_add_f32_e32 v0, v0, v14
	s_nop 1
	v_mov_b32_dpp v14, v0 row_half_mirror row_mask:0xf bank_mask:0xf
	s_nop 1
	v_mov_b32_dpp v14, v14 row_mirror row_mask:0xf bank_mask:0xf
	s_waitcnt lgkmcnt(0)
	v_add_f32_e32 v0, v0, v14
	ds_swizzle_b32 v14, v0 offset:swizzle(SWAP,16)
	s_and_saveexec_b64 s[12:13], s[34:35]
	s_cbranch_execz .LBB0_934
	s_waitcnt lgkmcnt(0)
	v_add_f32_e32 v16, v0, v14
	v_lshlrev_b32_e32 v0, 5, v80
	v_lshl_add_u64 v[14:15], s[86:87], 0, v[0:1]
	global_store_dword v[14:15], v16, off

; template <int K> __device__ __forceinline__ float shx(float v) { static_assert(K < 32, "use sum32"); return __int_as_float(__builtin_amdgcn_ds_swizzle(__float_as_int(v), (K << 10) | 0x1f)); }
; template <class TIn, class TOut, int ost, bool HAS_SS>
; __device__ __forceinline__ void causal_swa_block(const BlockRef<TIn, TOut>& cur_, const BlockRef<TIn, TOut>& nxt_, int skv, int W, char* lds, Seam<TIn>& S, int cbl  ) {
;     ...
;     for (int r = 0; r < 16; ++r) { const unsigned rowoff = ob0 + (unsigned)(((r & 3) + 8 * (r >> 2)) * ost * 2); float ss_ = 0.f;
; #pragma unroll
;         for (int d0 = 0; d0 < 4; ++d0) { const float v = o[d0][r] * rli[r]; ss_ += v * v;
;             const float vn = shx<1>(v);
;             if ((r32e & 1) == 0) *(unsigned*)(Ob + rowoff + d0 * 64) = cvtpk(v, vn); }
;         if (HAS_SS) { ss_ += shx<1>(ss_); ss_ += shx<2>(ss_); ss_ += shx<4>(ss_); ss_ += shx<8>(ss_); ss_ += shx<16>(ss_);
;             if (r32e == 0) *(float*)((char*)cur.SS + (unsigned)(wid * QBLK + 4 * hie + (r & 3) + 8 * (r >> 2)) * 32u) = ss_; }
.LBB0_942:
	s_or_b64 exec, exec, s[12:13]
	v_mul_f32_e32 v14, v48, v48
	v_fmac_f32_e32 v14, v0, v0
	v_fmac_f32_e32 v14, v33, v33
	v_fmac_f32_e32 v14, v17, v17
	s_nop 1
	v_mov_b32_dpp v0, v14 quad_perm:[1,0,3,2] row_mask:0xf bank_mask:0xf
	s_waitcnt lgkmcnt(0)
	v_add_f32_e32 v0, v14, v0
	s_nop 1
	v_mov_b32_dpp v14, v0 quad_perm:[2,3,0,1] row_mask:0xf bank_mask:0xf
	s_waitcnt lgkmcnt(0)
	v_add_f32_e32 v0, v0, v14
	s_nop 1
	v_mov_b32_dpp v14, v0 quad_perm:[3,2,1,0] row_mask:0xf bank_mask:0xf
	s_nop 1
	v_mov_b32_dpp v14, v14 row_half_mirror row_mask:0xf bank_mask:0xf
	s_waitcnt lgkmcnt(0)
	v_add_f32_e32 v0, v0, v14
	s_nop 1
	v_mov_b32_dpp v14, v0 row_half_mirror row_mask:0xf bank_mask:0xf
	s_nop 1
	v_mov_b32_dpp v14, v14 row_mirror row_mask:0xf bank_mask:0xf
	s_waitcnt lgkmcnt(0)
	v_add_f32_e32 v0, v0, v14
	ds_swizzle_b32 v14, v0 offset:swizzle(SWAP,16)
	s_and_saveexec_b64 s[12:13], s[34:35]
	s_cbranch_execz .LBB0_944
	s_waitcnt lgkmcnt(0)
	v_add_f32_e32 v17, v0, v14
	v_lshlrev_b32_e32 v0, 5, v16
	v_lshl_add_u64 v[14:15], s[86:87], 0, v[0:1]
	global_store_dword v[14:15], v17, off

; template <int K> __device__ __forceinline__ float shx(float v) { static_assert(K < 32, "use sum32"); return __int_as_float(__builtin_amdgcn_ds_swizzle(__float_as_int(v), (K << 10) | 0x1f)); }
; template <class TIn, class TOut, int ost, bool HAS_SS>
; __device__ __forceinline__ void causal_swa_block(const BlockRef<TIn, TOut>& cur_, const BlockRef<TIn, TOut>& nxt_, int skv, int W, char* lds, Seam<TIn>& S, int cbl  ) {
;     ...
;     for (int r = 0; r < 16; ++r) { const unsigned rowoff = ob0 + (unsigned)(((r & 3) + 8 * (r >> 2)) * ost * 2); float ss_ = 0.f;
; #pragma unroll
;         for (int d0 = 0; d0 < 4; ++d0) { const float v = o[d0][r] * rli[r]; ss_ += v * v;
;             const float vn = shx<1>(v);
;             if ((r32e & 1) == 0) *(unsigned*)(Ob + rowoff + d0 * 64) = cvtpk(v, vn); }
;         if (HAS_SS) { ss_ += shx<1>(ss_); ss_ += shx<2>(ss_); ss_ += shx<4>(ss_); ss_ += shx<8>(ss_); ss_ += shx<16>(ss_);
;             if (r32e == 0) *(float*)((char*)cur.SS + (unsigned)(wid * QBLK + 4 * hie + (r & 3) + 8 * (r >> 2)) * 32u) = ss_; }
.LBB0_952:
	s_or_b64 exec, exec, s[12:13]
	v_mul_f32_e32 v14, v32, v32
	v_fmac_f32_e32 v14, v0, v0
	v_fmac_f32_e32 v14, v33, v33
	v_fmac_f32_e32 v14, v17, v17
	s_nop 1
	v_mov_b32_dpp v0, v14 quad_perm:[1,0,3,2] row_mask:0xf bank_mask:0xf
	s_waitcnt lgkmcnt(0)
	v_add_f32_e32 v0, v14, v0
	s_nop 1
	v_mov_b32_dpp v14, v0 quad_perm:[2,3,0,1] row_mask:0xf bank_mask:0xf
	s_waitcnt lgkmcnt(0)
	v_add_f32_e32 v0, v0, v14
	s_nop 1
	v_mov_b32_dpp v14, v0 quad_perm:[3,2,1,0] row_mask:0xf bank_mask:0xf
	s_nop 1
	v_mov_b32_dpp v14, v14 row_half_mirror row_mask:0xf bank_mask:0xf
	s_waitcnt lgkmcnt(0)
	v_add_f32_e32 v0, v0, v14
	s_nop 1
	v_mov_b32_dpp v14, v0 row_half_mirror row_mask:0xf bank_mask:0xf
	s_nop 1
	v_mov_b32_dpp v14, v14 row_mirror row_mask:0xf bank_mask:0xf
	s_waitcnt lgkmcnt(0)
	v_add_f32_e32 v0, v0, v14
	ds_swizzle_b32 v14, v0 offset:swizzle(SWAP,16)
	s_and_saveexec_b64 s[12:13], s[34:35]
	s_cbranch_execz .LBB0_954
	s_waitcnt lgkmcnt(0)
	v_add_f32_e32 v17, v0, v14
	v_lshlrev_b32_e32 v0, 5, v16
	v_lshl_add_u64 v[14:15], s[86:87], 0, v[0:1]
	global_store_dword v[14:15], v17, off

; template <int K> __device__ __forceinline__ float shx(float v) { static_assert(K < 32, "use sum32"); return __int_as_float(__builtin_amdgcn_ds_swizzle(__float_as_int(v), (K << 10) | 0x1f)); }
; template <class TIn, class TOut, int ost, bool HAS_SS>
; __device__ __forceinline__ void causal_swa_block(const BlockRef<TIn, TOut>& cur_, const BlockRef<TIn, TOut>& nxt_, int skv, int W, char* lds, Seam<TIn>& S, int cbl  ) {
;     ...
;     for (int r = 0; r < 16; ++r) { const unsigned rowoff = ob0 + (unsigned)(((r & 3) + 8 * (r >> 2)) * ost * 2); float ss_ = 0.f;
; #pragma unroll
;         for (int d0 = 0; d0 < 4; ++d0) { const float v = o[d0][r] * rli[r]; ss_ += v * v;
;             const float vn = shx<1>(v);
;             if ((r32e & 1) == 0) *(unsigned*)(Ob + rowoff + d0 * 64) = cvtpk(v, vn); }
;         if (HAS_SS) { ss_ += shx<1>(ss_); ss_ += shx<2>(ss_); ss_ += shx<4>(ss_); ss_ += shx<8>(ss_); ss_ += shx<16>(ss_);
;             if (r32e == 0) *(float*)((char*)cur.SS + (unsigned)(wid * QBLK + 4 * hie + (r & 3) + 8 * (r >> 2)) * 32u) = ss_; }
.LBB0_962:
	s_or_b64 exec, exec, s[12:13]
	v_mul_f32_e32 v14, v18, v18
	v_fmac_f32_e32 v14, v0, v0
	v_fmac_f32_e32 v14, v32, v32
	v_fmac_f32_e32 v14, v17, v17
	s_nop 1
	v_mov_b32_dpp v0, v14 quad_perm:[1,0,3,2] row_mask:0xf bank_mask:0xf
	s_waitcnt lgkmcnt(0)
	v_add_f32_e32 v0, v14, v0
	s_nop 1
	v_mov_b32_dpp v14, v0 quad_perm:[2,3,0,1] row_mask:0xf bank_mask:0xf
	s_waitcnt lgkmcnt(0)
	v_add_f32_e32 v0, v0, v14
	s_nop 1
	v_mov_b32_dpp v14, v0 quad_perm:[3,2,1,0] row_mask:0xf bank_mask:0xf
	s_nop 1
	v_mov_b32_dpp v14, v14 row_half_mirror row_mask:0xf bank_mask:0xf
	s_waitcnt lgkmcnt(0)
	v_add_f32_e32 v0, v0, v14
	s_nop 1
	v_mov_b32_dpp v14, v0 row_half_mirror row_mask:0xf bank_mask:0xf
	s_nop 1
	v_mov_b32_dpp v14, v14 row_mirror row_mask:0xf bank_mask:0xf
	s_waitcnt lgkmcnt(0)
	v_add_f32_e32 v0, v0, v14
	ds_swizzle_b32 v14, v0 offset:swizzle(SWAP,16)
	s_and_saveexec_b64 s[12:13], s[34:35]
	s_cbranch_execz .LBB0_964
	s_waitcnt lgkmcnt(0)
	v_add_f32_e32 v17, v0, v14
	v_lshlrev_b32_e32 v0, 5, v16
	v_lshl_add_u64 v[14:15], s[86:87], 0, v[0:1]
	global_store_dword v[14:15], v17, off

; template <int K> __device__ __forceinline__ float shx(float v) { static_assert(K < 32, "use sum32"); return __int_as_float(__builtin_amdgcn_ds_swizzle(__float_as_int(v), (K << 10) | 0x1f)); }
; template <class TIn, class TOut, int ost, bool HAS_SS>
; __device__ __forceinline__ void causal_swa_block(const BlockRef<TIn, TOut>& cur_, const BlockRef<TIn, TOut>& nxt_, int skv, int W, char* lds, Seam<TIn>& S, int cbl  ) {
;     ...
;     for (int r = 0; r < 16; ++r) { const unsigned rowoff = ob0 + (unsigned)(((r & 3) + 8 * (r >> 2)) * ost * 2); float ss_ = 0.f;
; #pragma unroll
;         for (int d0 = 0; d0 < 4; ++d0) { const float v = o[d0][r] * rli[r]; ss_ += v * v;
;             const float vn = shx<1>(v);
;             if ((r32e & 1) == 0) *(unsigned*)(Ob + rowoff + d0 * 64) = cvtpk(v, vn); }
;         if (HAS_SS) { ss_ += shx<1>(ss_); ss_ += shx<2>(ss_); ss_ += shx<4>(ss_); ss_ += shx<8>(ss_); ss_ += shx<16>(ss_);
;             if (r32e == 0) *(float*)((char*)cur.SS + (unsigned)(wid * QBLK + 4 * hie + (r & 3) + 8 * (r >> 2)) * 32u) = ss_; }
.LBB0_972:
	s_or_b64 exec, exec, s[12:13]
	v_mul_f32_e32 v14, v17, v17
	v_fmac_f32_e32 v14, v0, v0
	v_fmac_f32_e32 v14, v18, v18
	v_fmac_f32_e32 v14, v16, v16
	s_nop 1
	v_mov_b32_dpp v0, v14 quad_perm:[1,0,3,2] row_mask:0xf bank_mask:0xf
	s_waitcnt lgkmcnt(0)
	v_add_f32_e32 v0, v14, v0
	s_nop 1
	v_mov_b32_dpp v14, v0 quad_perm:[2,3,0,1] row_mask:0xf bank_mask:0xf
	s_waitcnt lgkmcnt(0)
	v_add_f32_e32 v0, v0, v14
	s_nop 1
	v_mov_b32_dpp v14, v0 quad_perm:[3,2,1,0] row_mask:0xf bank_mask:0xf
	s_nop 1
	v_mov_b32_dpp v14, v14 row_half_mirror row_mask:0xf bank_mask:0xf
	s_waitcnt lgkmcnt(0)
	v_add_f32_e32 v0, v0, v14
	s_nop 1
	v_mov_b32_dpp v14, v0 row_half_mirror row_mask:0xf bank_mask:0xf
	s_nop 1
	v_mov_b32_dpp v14, v14 row_mirror row_mask:0xf bank_mask:0xf
	s_waitcnt lgkmcnt(0)
	v_add_f32_e32 v0, v0, v14
	ds_swizzle_b32 v14, v0 offset:swizzle(SWAP,16)
	s_and_saveexec_b64 s[12:13], s[34:35]
	s_cbranch_execz .LBB0_974
	s_waitcnt lgkmcnt(0)
	v_add_f32_e32 v16, v0, v14
	v_lshlrev_b32_e32 v0, 5, v10
	v_lshl_add_u64 v[14:15], s[86:87], 0, v[0:1]
	global_store_dword v[14:15], v16, off

; template <int K> __device__ __forceinline__ float shx(float v) { static_assert(K < 32, "use sum32"); return __int_as_float(__builtin_amdgcn_ds_swizzle(__float_as_int(v), (K << 10) | 0x1f)); }
; template <class TIn, class TOut, int ost, bool HAS_SS>
; __device__ __forceinline__ void causal_swa_block(const BlockRef<TIn, TOut>& cur_, const BlockRef<TIn, TOut>& nxt_, int skv, int W, char* lds, Seam<TIn>& S, int cbl  ) {
;     ...
;     for (int r = 0; r < 16; ++r) { const unsigned rowoff = ob0 + (unsigned)(((r & 3) + 8 * (r >> 2)) * ost * 2); float ss_ = 0.f;
; #pragma unroll
;         for (int d0 = 0; d0 < 4; ++d0) { const float v = o[d0][r] * rli[r]; ss_ += v * v;
;             const float vn = shx<1>(v);
;             if ((r32e & 1) == 0) *(unsigned*)(Ob + rowoff + d0 * 64) = cvtpk(v, vn); }
;         if (HAS_SS) { ss_ += shx<1>(ss_); ss_ += shx<2>(ss_); ss_ += shx<4>(ss_); ss_ += shx<8>(ss_); ss_ += shx<16>(ss_);
;             if (r32e == 0) *(float*)((char*)cur.SS + (unsigned)(wid * QBLK + 4 * hie + (r & 3) + 8 * (r >> 2)) * 32u) = ss_; }
.LBB0_982:
	s_or_b64 exec, exec, s[12:13]
	v_mul_f32_e32 v10, v16, v16
	v_fmac_f32_e32 v10, v0, v0
	v_fmac_f32_e32 v10, v17, v17
	v_fmac_f32_e32 v10, v15, v15
	s_nop 1
	v_mov_b32_dpp v0, v10 quad_perm:[1,0,3,2] row_mask:0xf bank_mask:0xf
	s_waitcnt lgkmcnt(0)
	v_add_f32_e32 v0, v10, v0
	s_nop 1
	v_mov_b32_dpp v10, v0 quad_perm:[2,3,0,1] row_mask:0xf bank_mask:0xf
	s_waitcnt lgkmcnt(0)
	v_add_f32_e32 v0, v0, v10
	s_nop 1
	v_mov_b32_dpp v10, v0 quad_perm:[3,2,1,0] row_mask:0xf bank_mask:0xf
	s_nop 1
	v_mov_b32_dpp v10, v10 row_half_mirror row_mask:0xf bank_mask:0xf
	s_waitcnt lgkmcnt(0)
	v_add_f32_e32 v0, v0, v10
	s_nop 1
	v_mov_b32_dpp v10, v0 row_half_mirror row_mask:0xf bank_mask:0xf
	s_nop 1
	v_mov_b32_dpp v10, v10 row_mirror row_mask:0xf bank_mask:0xf
	s_waitcnt lgkmcnt(0)
	v_add_f32_e32 v0, v0, v10
	ds_swizzle_b32 v10, v0 offset:swizzle(SWAP,16)
	s_and_saveexec_b64 s[12:13], s[34:35]
	s_cbranch_execz .LBB0_984
	s_waitcnt lgkmcnt(0)
	v_add_f32_e32 v15, v0, v10
	v_lshlrev_b32_e32 v0, 5, v14
	v_lshl_add_u64 v[10:11], s[86:87], 0, v[0:1]
	global_store_dword v[10:11], v15, off

; template <int K> __device__ __forceinline__ float shx(float v) { static_assert(K < 32, "use sum32"); return __int_as_float(__builtin_amdgcn_ds_swizzle(__float_as_int(v), (K << 10) | 0x1f)); }
; template <class TIn, class TOut, int ost, bool HAS_SS>
; __device__ __forceinline__ void causal_swa_block(const BlockRef<TIn, TOut>& cur_, const BlockRef<TIn, TOut>& nxt_, int skv, int W, char* lds, Seam<TIn>& S, int cbl  ) {
;     ...
;     for (int r = 0; r < 16; ++r) { const unsigned rowoff = ob0 + (unsigned)(((r & 3) + 8 * (r >> 2)) * ost * 2); float ss_ = 0.f;
; #pragma unroll
;         for (int d0 = 0; d0 < 4; ++d0) { const float v = o[d0][r] * rli[r]; ss_ += v * v;
;             const float vn = shx<1>(v);
;             if ((r32e & 1) == 0) *(unsigned*)(Ob + rowoff + d0 * 64) = cvtpk(v, vn); }
;         if (HAS_SS) { ss_ += shx<1>(ss_); ss_ += shx<2>(ss_); ss_ += shx<4>(ss_); ss_ += shx<8>(ss_); ss_ += shx<16>(ss_);
;             if (r32e == 0) *(float*)((char*)cur.SS + (unsigned)(wid * QBLK + 4 * hie + (r & 3) + 8 * (r >> 2)) * 32u) = ss_; }
.LBB0_992:
	s_or_b64 exec, exec, s[12:13]
	v_mul_f32_e32 v10, v15, v15
	v_fmac_f32_e32 v10, v0, v0
	v_fmac_f32_e32 v10, v16, v16
	v_fmac_f32_e32 v10, v14, v14
	s_nop 1
	v_mov_b32_dpp v0, v10 quad_perm:[1,0,3,2] row_mask:0xf bank_mask:0xf
	s_waitcnt lgkmcnt(0)
	v_add_f32_e32 v0, v10, v0
	s_nop 1
	v_mov_b32_dpp v10, v0 quad_perm:[2,3,0,1] row_mask:0xf bank_mask:0xf
	s_waitcnt lgkmcnt(0)
	v_add_f32_e32 v0, v0, v10
	s_nop 1
	v_mov_b32_dpp v10, v0 quad_perm:[3,2,1,0] row_mask:0xf bank_mask:0xf
	s_nop 1
	v_mov_b32_dpp v10, v10 row_half_mirror row_mask:0xf bank_mask:0xf
	s_waitcnt lgkmcnt(0)
	v_add_f32_e32 v0, v0, v10
	s_nop 1
	v_mov_b32_dpp v10, v0 row_half_mirror row_mask:0xf bank_mask:0xf
	s_nop 1
	v_mov_b32_dpp v10, v10 row_mirror row_mask:0xf bank_mask:0xf
	s_waitcnt lgkmcnt(0)
	v_add_f32_e32 v0, v0, v10
	ds_swizzle_b32 v10, v0 offset:swizzle(SWAP,16)
	s_and_saveexec_b64 s[12:13], s[34:35]
	s_cbranch_execz .LBB0_994
	s_waitcnt lgkmcnt(0)
	v_add_f32_e32 v14, v0, v10
	v_lshlrev_b32_e32 v0, 5, v12
	v_lshl_add_u64 v[10:11], s[86:87], 0, v[0:1]
	global_store_dword v[10:11], v14, off

; template <int K> __device__ __forceinline__ float shx(float v) { static_assert(K < 32, "use sum32"); return __int_as_float(__builtin_amdgcn_ds_swizzle(__float_as_int(v), (K << 10) | 0x1f)); }
; template <class TIn, class TOut, int ost, bool HAS_SS>
; __device__ __forceinline__ void causal_swa_block(const BlockRef<TIn, TOut>& cur_, const BlockRef<TIn, TOut>& nxt_, int skv, int W, char* lds, Seam<TIn>& S, int cbl  ) {
;     ...
;     for (int r = 0; r < 16; ++r) { const unsigned rowoff = ob0 + (unsigned)(((r & 3) + 8 * (r >> 2)) * ost * 2); float ss_ = 0.f;
; #pragma unroll
;         for (int d0 = 0; d0 < 4; ++d0) { const float v = o[d0][r] * rli[r]; ss_ += v * v;
;             const float vn = shx<1>(v);
;             if ((r32e & 1) == 0) *(unsigned*)(Ob + rowoff + d0 * 64) = cvtpk(v, vn); }
;         if (HAS_SS) { ss_ += shx<1>(ss_); ss_ += shx<2>(ss_); ss_ += shx<4>(ss_); ss_ += shx<8>(ss_); ss_ += shx<16>(ss_);
;             if (r32e == 0) *(float*)((char*)cur.SS + (unsigned)(wid * QBLK + 4 * hie + (r & 3) + 8 * (r >> 2)) * 32u) = ss_; }
.LBB0_1002:
	s_or_b64 exec, exec, s[12:13]
	v_mul_f32_e32 v10, v14, v14
	v_fmac_f32_e32 v10, v0, v0
	v_fmac_f32_e32 v10, v15, v15
	v_fmac_f32_e32 v10, v13, v13
	s_nop 1
	v_mov_b32_dpp v0, v10 quad_perm:[1,0,3,2] row_mask:0xf bank_mask:0xf
	s_waitcnt lgkmcnt(0)
	v_add_f32_e32 v0, v10, v0
	s_nop 1
	v_mov_b32_dpp v10, v0 quad_perm:[2,3,0,1] row_mask:0xf bank_mask:0xf
	s_waitcnt lgkmcnt(0)
	v_add_f32_e32 v0, v0, v10
	s_nop 1
	v_mov_b32_dpp v10, v0 quad_perm:[3,2,1,0] row_mask:0xf bank_mask:0xf
	s_nop 1
	v_mov_b32_dpp v10, v10 row_half_mirror row_mask:0xf bank_mask:0xf
	s_waitcnt lgkmcnt(0)
	v_add_f32_e32 v0, v0, v10
	s_nop 1
	v_mov_b32_dpp v10, v0 row_half_mirror row_mask:0xf bank_mask:0xf
	s_nop 1
	v_mov_b32_dpp v10, v10 row_mirror row_mask:0xf bank_mask:0xf
	s_waitcnt lgkmcnt(0)
	v_add_f32_e32 v0, v0, v10
	ds_swizzle_b32 v10, v0 offset:swizzle(SWAP,16)
	s_and_saveexec_b64 s[12:13], s[34:35]
	s_cbranch_execz .LBB0_1004
	s_waitcnt lgkmcnt(0)
	v_add_f32_e32 v13, v0, v10
	v_lshlrev_b32_e32 v0, 5, v12
	v_lshl_add_u64 v[10:11], s[86:87], 0, v[0:1]
	global_store_dword v[10:11], v13, off

; template <int K> __device__ __forceinline__ float shx(float v) { static_assert(K < 32, "use sum32"); return __int_as_float(__builtin_amdgcn_ds_swizzle(__float_as_int(v), (K << 10) | 0x1f)); }
; template <class TIn, class TOut, int ost, bool HAS_SS>
; __device__ __forceinline__ void causal_swa_block(const BlockRef<TIn, TOut>& cur_, const BlockRef<TIn, TOut>& nxt_, int skv, int W, char* lds, Seam<TIn>& S, int cbl  ) {
;     ...
;     for (int r = 0; r < 16; ++r) { const unsigned rowoff = ob0 + (unsigned)(((r & 3) + 8 * (r >> 2)) * ost * 2); float ss_ = 0.f;
; #pragma unroll
;         for (int d0 = 0; d0 < 4; ++d0) { const float v = o[d0][r] * rli[r]; ss_ += v * v;
;             const float vn = shx<1>(v);
;             if ((r32e & 1) == 0) *(unsigned*)(Ob + rowoff + d0 * 64) = cvtpk(v, vn); }
;         if (HAS_SS) { ss_ += shx<1>(ss_); ss_ += shx<2>(ss_); ss_ += shx<4>(ss_); ss_ += shx<8>(ss_); ss_ += shx<16>(ss_);
;             if (r32e == 0) *(float*)((char*)cur.SS + (unsigned)(wid * QBLK + 4 * hie + (r & 3) + 8 * (r >> 2)) * 32u) = ss_; }
.LBB0_1012:
	s_or_b64 exec, exec, s[12:13]
	v_mul_f32_e32 v10, v13, v13
	v_fmac_f32_e32 v10, v0, v0
	v_fmac_f32_e32 v10, v14, v14
	v_fmac_f32_e32 v10, v12, v12
	s_nop 1
	v_mov_b32_dpp v0, v10 quad_perm:[1,0,3,2] row_mask:0xf bank_mask:0xf
	s_waitcnt lgkmcnt(0)
	v_add_f32_e32 v0, v10, v0
	s_nop 1
	v_mov_b32_dpp v10, v0 quad_perm:[2,3,0,1] row_mask:0xf bank_mask:0xf
	s_waitcnt lgkmcnt(0)
	v_add_f32_e32 v0, v0, v10
	s_nop 1
	v_mov_b32_dpp v10, v0 quad_perm:[3,2,1,0] row_mask:0xf bank_mask:0xf
	s_nop 1
	v_mov_b32_dpp v10, v10 row_half_mirror row_mask:0xf bank_mask:0xf
	s_waitcnt lgkmcnt(0)
	v_add_f32_e32 v0, v0, v10
	s_nop 1
	v_mov_b32_dpp v10, v0 row_half_mirror row_mask:0xf bank_mask:0xf
	s_nop 1
	v_mov_b32_dpp v10, v10 row_mirror row_mask:0xf bank_mask:0xf
	s_waitcnt lgkmcnt(0)
	v_add_f32_e32 v0, v0, v10
	ds_swizzle_b32 v10, v0 offset:swizzle(SWAP,16)
	s_and_saveexec_b64 s[12:13], s[34:35]
	s_cbranch_execz .LBB0_1014
	s_waitcnt lgkmcnt(0)
	v_add_f32_e32 v12, v0, v10
	v_lshlrev_b32_e32 v0, 5, v6
	v_lshl_add_u64 v[10:11], s[86:87], 0, v[0:1]
	global_store_dword v[10:11], v12, off

; template <int K> __device__ __forceinline__ float shx(float v) { static_assert(K < 32, "use sum32"); return __int_as_float(__builtin_amdgcn_ds_swizzle(__float_as_int(v), (K << 10) | 0x1f)); }
; template <class TIn, class TOut, int ost, bool HAS_SS>
; __device__ __forceinline__ void causal_swa_block(const BlockRef<TIn, TOut>& cur_, const BlockRef<TIn, TOut>& nxt_, int skv, int W, char* lds, Seam<TIn>& S, int cbl  ) {
;     ...
;     for (int r = 0; r < 16; ++r) { const unsigned rowoff = ob0 + (unsigned)(((r & 3) + 8 * (r >> 2)) * ost * 2); float ss_ = 0.f;
; #pragma unroll
;         for (int d0 = 0; d0 < 4; ++d0) { const float v = o[d0][r] * rli[r]; ss_ += v * v;
;             const float vn = shx<1>(v);
;             if ((r32e & 1) == 0) *(unsigned*)(Ob + rowoff + d0 * 64) = cvtpk(v, vn); }
;         if (HAS_SS) { ss_ += shx<1>(ss_); ss_ += shx<2>(ss_); ss_ += shx<4>(ss_); ss_ += shx<8>(ss_); ss_ += shx<16>(ss_);
;             if (r32e == 0) *(float*)((char*)cur.SS + (unsigned)(wid * QBLK + 4 * hie + (r & 3) + 8 * (r >> 2)) * 32u) = ss_; }
.LBB0_1022:
	s_or_b64 exec, exec, s[12:13]
	v_mul_f32_e32 v6, v12, v12
	v_fmac_f32_e32 v6, v0, v0
	v_fmac_f32_e32 v6, v13, v13
	v_fmac_f32_e32 v6, v11, v11
	s_nop 1
	v_mov_b32_dpp v0, v6 quad_perm:[1,0,3,2] row_mask:0xf bank_mask:0xf
	s_waitcnt lgkmcnt(0)
	v_add_f32_e32 v0, v6, v0
	s_nop 1
	v_mov_b32_dpp v6, v0 quad_perm:[2,3,0,1] row_mask:0xf bank_mask:0xf
	s_waitcnt lgkmcnt(0)
	v_add_f32_e32 v0, v0, v6
	s_nop 1
	v_mov_b32_dpp v6, v0 quad_perm:[3,2,1,0] row_mask:0xf bank_mask:0xf
	s_nop 1
	v_mov_b32_dpp v6, v6 row_half_mirror row_mask:0xf bank_mask:0xf
	s_waitcnt lgkmcnt(0)
	v_add_f32_e32 v0, v0, v6
	s_nop 1
	v_mov_b32_dpp v6, v0 row_half_mirror row_mask:0xf bank_mask:0xf
	s_nop 1
	v_mov_b32_dpp v6, v6 row_mirror row_mask:0xf bank_mask:0xf
	s_waitcnt lgkmcnt(0)
	v_add_f32_e32 v0, v0, v6
	ds_swizzle_b32 v6, v0 offset:swizzle(SWAP,16)
	s_and_saveexec_b64 s[12:13], s[34:35]
	s_cbranch_execz .LBB0_1024
	s_waitcnt lgkmcnt(0)
	v_add_f32_e32 v11, v0, v6
	v_lshlrev_b32_e32 v0, 5, v10
	v_lshl_add_u64 v[6:7], s[86:87], 0, v[0:1]
	global_store_dword v[6:7], v11, off

; template <int K> __device__ __forceinline__ float shx(float v) { static_assert(K < 32, "use sum32"); return __int_as_float(__builtin_amdgcn_ds_swizzle(__float_as_int(v), (K << 10) | 0x1f)); }
; template <class TIn, class TOut, int ost, bool HAS_SS>
; __device__ __forceinline__ void causal_swa_block(const BlockRef<TIn, TOut>& cur_, const BlockRef<TIn, TOut>& nxt_, int skv, int W, char* lds, Seam<TIn>& S, int cbl  ) {
;     ...
;     for (int r = 0; r < 16; ++r) { const unsigned rowoff = ob0 + (unsigned)(((r & 3) + 8 * (r >> 2)) * ost * 2); float ss_ = 0.f;
; #pragma unroll
;         for (int d0 = 0; d0 < 4; ++d0) { const float v = o[d0][r] * rli[r]; ss_ += v * v;
;             const float vn = shx<1>(v);
;             if ((r32e & 1) == 0) *(unsigned*)(Ob + rowoff + d0 * 64) = cvtpk(v, vn); }
;         if (HAS_SS) { ss_ += shx<1>(ss_); ss_ += shx<2>(ss_); ss_ += shx<4>(ss_); ss_ += shx<8>(ss_); ss_ += shx<16>(ss_);
;             if (r32e == 0) *(float*)((char*)cur.SS + (unsigned)(wid * QBLK + 4 * hie + (r & 3) + 8 * (r >> 2)) * 32u) = ss_; }
.LBB0_1032:
	s_or_b64 exec, exec, s[12:13]
	v_mul_f32_e32 v6, v11, v11
	v_fmac_f32_e32 v6, v0, v0
	v_fmac_f32_e32 v6, v12, v12
	v_fmac_f32_e32 v6, v10, v10
	s_nop 1
	v_mov_b32_dpp v0, v6 quad_perm:[1,0,3,2] row_mask:0xf bank_mask:0xf
	s_waitcnt lgkmcnt(0)
	v_add_f32_e32 v0, v6, v0
	s_nop 1
	v_mov_b32_dpp v6, v0 quad_perm:[2,3,0,1] row_mask:0xf bank_mask:0xf
	s_waitcnt lgkmcnt(0)
	v_add_f32_e32 v0, v0, v6
	s_nop 1
	v_mov_b32_dpp v6, v0 quad_perm:[3,2,1,0] row_mask:0xf bank_mask:0xf
	s_nop 1
	v_mov_b32_dpp v6, v6 row_half_mirror row_mask:0xf bank_mask:0xf
	s_waitcnt lgkmcnt(0)
	v_add_f32_e32 v0, v0, v6
	s_nop 1
	v_mov_b32_dpp v6, v0 row_half_mirror row_mask:0xf bank_mask:0xf
	s_nop 1
	v_mov_b32_dpp v6, v6 row_mirror row_mask:0xf bank_mask:0xf
	s_waitcnt lgkmcnt(0)
	v_add_f32_e32 v0, v0, v6
	ds_swizzle_b32 v6, v0 offset:swizzle(SWAP,16)
	s_and_saveexec_b64 s[12:13], s[34:35]
	s_cbranch_execz .LBB0_1034
	s_waitcnt lgkmcnt(0)
	v_add_f32_e32 v10, v0, v6
	v_lshlrev_b32_e32 v0, 5, v8
	v_lshl_add_u64 v[6:7], s[86:87], 0, v[0:1]
	global_store_dword v[6:7], v10, off

; template <int K> __device__ __forceinline__ float shx(float v) { static_assert(K < 32, "use sum32"); return __int_as_float(__builtin_amdgcn_ds_swizzle(__float_as_int(v), (K << 10) | 0x1f)); }
; template <class TIn, class TOut, int ost, bool HAS_SS>
; __device__ __forceinline__ void causal_swa_block(const BlockRef<TIn, TOut>& cur_, const BlockRef<TIn, TOut>& nxt_, int skv, int W, char* lds, Seam<TIn>& S, int cbl  ) {
;     ...
;     for (int r = 0; r < 16; ++r) { const unsigned rowoff = ob0 + (unsigned)(((r & 3) + 8 * (r >> 2)) * ost * 2); float ss_ = 0.f;
; #pragma unroll
;         for (int d0 = 0; d0 < 4; ++d0) { const float v = o[d0][r] * rli[r]; ss_ += v * v;
;             const float vn = shx<1>(v);
;             if ((r32e & 1) == 0) *(unsigned*)(Ob + rowoff + d0 * 64) = cvtpk(v, vn); }
;         if (HAS_SS) { ss_ += shx<1>(ss_); ss_ += shx<2>(ss_); ss_ += shx<4>(ss_); ss_ += shx<8>(ss_); ss_ += shx<16>(ss_);
;             if (r32e == 0) *(float*)((char*)cur.SS + (unsigned)(wid * QBLK + 4 * hie + (r & 3) + 8 * (r >> 2)) * 32u) = ss_; }
.LBB0_1042:
	s_or_b64 exec, exec, s[12:13]
	v_mul_f32_e32 v6, v10, v10
	v_fmac_f32_e32 v6, v0, v0
	v_fmac_f32_e32 v6, v11, v11
	v_fmac_f32_e32 v6, v9, v9
	s_nop 1
	v_mov_b32_dpp v0, v6 quad_perm:[1,0,3,2] row_mask:0xf bank_mask:0xf
	s_waitcnt lgkmcnt(0)
	v_add_f32_e32 v0, v6, v0
	s_nop 1
	v_mov_b32_dpp v6, v0 quad_perm:[2,3,0,1] row_mask:0xf bank_mask:0xf
	s_waitcnt lgkmcnt(0)
	v_add_f32_e32 v0, v0, v6
	s_nop 1
	v_mov_b32_dpp v6, v0 quad_perm:[3,2,1,0] row_mask:0xf bank_mask:0xf
	s_nop 1
	v_mov_b32_dpp v6, v6 row_half_mirror row_mask:0xf bank_mask:0xf
	s_waitcnt lgkmcnt(0)
	v_add_f32_e32 v0, v0, v6
	s_nop 1
	v_mov_b32_dpp v6, v0 row_half_mirror row_mask:0xf bank_mask:0xf
	s_nop 1
	v_mov_b32_dpp v6, v6 row_mirror row_mask:0xf bank_mask:0xf
	s_waitcnt lgkmcnt(0)
	v_add_f32_e32 v0, v0, v6
	ds_swizzle_b32 v6, v0 offset:swizzle(SWAP,16)
	s_and_saveexec_b64 s[12:13], s[34:35]
	s_cbranch_execz .LBB0_1044
	s_waitcnt lgkmcnt(0)
	v_add_f32_e32 v9, v0, v6
	v_lshlrev_b32_e32 v0, 5, v8
	v_lshl_add_u64 v[6:7], s[86:87], 0, v[0:1]
	global_store_dword v[6:7], v9, off

; template <int K> __device__ __forceinline__ float shx(float v) { static_assert(K < 32, "use sum32"); return __int_as_float(__builtin_amdgcn_ds_swizzle(__float_as_int(v), (K << 10) | 0x1f)); }
; template <class TIn, class TOut, int ost, bool HAS_SS>
; __device__ __forceinline__ void causal_swa_block(const BlockRef<TIn, TOut>& cur_, const BlockRef<TIn, TOut>& nxt_, int skv, int W, char* lds, Seam<TIn>& S, int cbl  ) {
;     ...
;     for (int r = 0; r < 16; ++r) { const unsigned rowoff = ob0 + (unsigned)(((r & 3) + 8 * (r >> 2)) * ost * 2); float ss_ = 0.f;
; #pragma unroll
;         for (int d0 = 0; d0 < 4; ++d0) { const float v = o[d0][r] * rli[r]; ss_ += v * v;
;             const float vn = shx<1>(v);
;             if ((r32e & 1) == 0) *(unsigned*)(Ob + rowoff + d0 * 64) = cvtpk(v, vn); }
;         if (HAS_SS) { ss_ += shx<1>(ss_); ss_ += shx<2>(ss_); ss_ += shx<4>(ss_); ss_ += shx<8>(ss_); ss_ += shx<16>(ss_);
;             if (r32e == 0) *(float*)((char*)cur.SS + (unsigned)(wid * QBLK + 4 * hie + (r & 3) + 8 * (r >> 2)) * 32u) = ss_; }
.LBB0_1052:
	s_or_b64 exec, exec, s[12:13]
	v_mul_f32_e32 v6, v9, v9
	v_fmac_f32_e32 v6, v0, v0
	v_fmac_f32_e32 v6, v10, v10
	v_fmac_f32_e32 v6, v8, v8
	s_nop 1
	v_mov_b32_dpp v0, v6 quad_perm:[1,0,3,2] row_mask:0xf bank_mask:0xf
	s_waitcnt lgkmcnt(0)
	v_add_f32_e32 v0, v6, v0
	s_nop 1
	v_mov_b32_dpp v6, v0 quad_perm:[2,3,0,1] row_mask:0xf bank_mask:0xf
	s_waitcnt lgkmcnt(0)
	v_add_f32_e32 v0, v0, v6
	s_nop 1
	v_mov_b32_dpp v6, v0 quad_perm:[3,2,1,0] row_mask:0xf bank_mask:0xf
	s_nop 1
	v_mov_b32_dpp v6, v6 row_half_mirror row_mask:0xf bank_mask:0xf
	s_waitcnt lgkmcnt(0)
	v_add_f32_e32 v0, v0, v6
	s_nop 1
	v_mov_b32_dpp v6, v0 row_half_mirror row_mask:0xf bank_mask:0xf
	s_nop 1
	v_mov_b32_dpp v6, v6 row_mirror row_mask:0xf bank_mask:0xf
	s_waitcnt lgkmcnt(0)
	v_add_f32_e32 v0, v0, v6
	ds_swizzle_b32 v6, v0 offset:swizzle(SWAP,16)
	s_and_saveexec_b64 s[12:13], s[34:35]
	s_cbranch_execz .LBB0_1054
	s_waitcnt lgkmcnt(0)
	v_add_f32_e32 v8, v0, v6
	v_lshlrev_b32_e32 v0, 5, v2
	v_lshl_add_u64 v[6:7], s[86:87], 0, v[0:1]
	global_store_dword v[6:7], v8, off

; template <int K> __device__ __forceinline__ float shx(float v) { static_assert(K < 32, "use sum32"); return __int_as_float(__builtin_amdgcn_ds_swizzle(__float_as_int(v), (K << 10) | 0x1f)); }
; template <class TIn, class TOut, int ost, bool HAS_SS>
; __device__ __forceinline__ void causal_swa_block(const BlockRef<TIn, TOut>& cur_, const BlockRef<TIn, TOut>& nxt_, int skv, int W, char* lds, Seam<TIn>& S, int cbl  ) {
;     ...
;     for (int r = 0; r < 16; ++r) { const unsigned rowoff = ob0 + (unsigned)(((r & 3) + 8 * (r >> 2)) * ost * 2); float ss_ = 0.f;
; #pragma unroll
;         for (int d0 = 0; d0 < 4; ++d0) { const float v = o[d0][r] * rli[r]; ss_ += v * v;
;             const float vn = shx<1>(v);
;             if ((r32e & 1) == 0) *(unsigned*)(Ob + rowoff + d0 * 64) = cvtpk(v, vn); }
;         if (HAS_SS) { ss_ += shx<1>(ss_); ss_ += shx<2>(ss_); ss_ += shx<4>(ss_); ss_ += shx<8>(ss_); ss_ += shx<16>(ss_);
;             if (r32e == 0) *(float*)((char*)cur.SS + (unsigned)(wid * QBLK + 4 * hie + (r & 3) + 8 * (r >> 2)) * 32u) = ss_; }
.LBB0_1062:
	s_or_b64 exec, exec, s[12:13]
	v_mul_f32_e32 v2, v8, v8
	v_fmac_f32_e32 v2, v0, v0
	v_fmac_f32_e32 v2, v9, v9
	v_fmac_f32_e32 v2, v7, v7
	s_nop 1
	v_mov_b32_dpp v0, v2 quad_perm:[1,0,3,2] row_mask:0xf bank_mask:0xf
	s_waitcnt lgkmcnt(0)
	v_add_f32_e32 v0, v2, v0
	s_nop 1
	v_mov_b32_dpp v2, v0 quad_perm:[2,3,0,1] row_mask:0xf bank_mask:0xf
	s_waitcnt lgkmcnt(0)
	v_add_f32_e32 v0, v0, v2
	s_nop 1
	v_mov_b32_dpp v2, v0 quad_perm:[3,2,1,0] row_mask:0xf bank_mask:0xf
	s_nop 1
	v_mov_b32_dpp v2, v2 row_half_mirror row_mask:0xf bank_mask:0xf
	s_waitcnt lgkmcnt(0)
	v_add_f32_e32 v0, v0, v2
	s_nop 1
	v_mov_b32_dpp v2, v0 row_half_mirror row_mask:0xf bank_mask:0xf
	s_nop 1
	v_mov_b32_dpp v2, v2 row_mirror row_mask:0xf bank_mask:0xf
	s_waitcnt lgkmcnt(0)
	v_add_f32_e32 v0, v0, v2
	ds_swizzle_b32 v2, v0 offset:swizzle(SWAP,16)
	s_and_saveexec_b64 s[12:13], s[34:35]
	s_cbranch_execz .LBB0_1064
	s_waitcnt lgkmcnt(0)
	v_add_f32_e32 v7, v0, v2
	v_lshlrev_b32_e32 v0, 5, v6
	v_lshl_add_u64 v[2:3], s[86:87], 0, v[0:1]
	global_store_dword v[2:3], v7, off

; template <int K> __device__ __forceinline__ float shx(float v) { static_assert(K < 32, "use sum32"); return __int_as_float(__builtin_amdgcn_ds_swizzle(__float_as_int(v), (K << 10) | 0x1f)); }
; template <class TIn, class TOut, int ost, bool HAS_SS>
; __device__ __forceinline__ void causal_swa_block(const BlockRef<TIn, TOut>& cur_, const BlockRef<TIn, TOut>& nxt_, int skv, int W, char* lds, Seam<TIn>& S, int cbl  ) {
;     ...
;     for (int r = 0; r < 16; ++r) { const unsigned rowoff = ob0 + (unsigned)(((r & 3) + 8 * (r >> 2)) * ost * 2); float ss_ = 0.f;
; #pragma unroll
;         for (int d0 = 0; d0 < 4; ++d0) { const float v = o[d0][r] * rli[r]; ss_ += v * v;
;             const float vn = shx<1>(v);
;             if ((r32e & 1) == 0) *(unsigned*)(Ob + rowoff + d0 * 64) = cvtpk(v, vn); }
;         if (HAS_SS) { ss_ += shx<1>(ss_); ss_ += shx<2>(ss_); ss_ += shx<4>(ss_); ss_ += shx<8>(ss_); ss_ += shx<16>(ss_);
;             if (r32e == 0) *(float*)((char*)cur.SS + (unsigned)(wid * QBLK + 4 * hie + (r & 3) + 8 * (r >> 2)) * 32u) = ss_; }
.LBB0_1072:
	s_or_b64 exec, exec, s[12:13]
	v_mul_f32_e32 v2, v7, v7
	v_fmac_f32_e32 v2, v0, v0
	v_fmac_f32_e32 v2, v8, v8
	v_fmac_f32_e32 v2, v6, v6
	s_nop 1
	v_mov_b32_dpp v0, v2 quad_perm:[1,0,3,2] row_mask:0xf bank_mask:0xf
	s_waitcnt lgkmcnt(0)
	v_add_f32_e32 v0, v2, v0
	s_nop 1
	v_mov_b32_dpp v2, v0 quad_perm:[2,3,0,1] row_mask:0xf bank_mask:0xf
	s_waitcnt lgkmcnt(0)
	v_add_f32_e32 v0, v0, v2
	s_nop 1
	v_mov_b32_dpp v2, v0 quad_perm:[3,2,1,0] row_mask:0xf bank_mask:0xf
	s_nop 1
	v_mov_b32_dpp v2, v2 row_half_mirror row_mask:0xf bank_mask:0xf
	s_waitcnt lgkmcnt(0)
	v_add_f32_e32 v0, v0, v2
	s_nop 1
	v_mov_b32_dpp v2, v0 row_half_mirror row_mask:0xf bank_mask:0xf
	s_nop 1
	v_mov_b32_dpp v2, v2 row_mirror row_mask:0xf bank_mask:0xf
	s_waitcnt lgkmcnt(0)
	v_add_f32_e32 v0, v0, v2
	ds_swizzle_b32 v2, v0 offset:swizzle(SWAP,16)
	s_and_saveexec_b64 s[12:13], s[34:35]
	s_cbranch_execz .LBB0_1074
	s_waitcnt lgkmcnt(0)
	v_add_f32_e32 v6, v0, v2
	v_lshlrev_b32_e32 v0, 5, v4
	v_lshl_add_u64 v[2:3], s[86:87], 0, v[0:1]
	global_store_dword v[2:3], v6, off

; template <int K> __device__ __forceinline__ float shx(float v) { static_assert(K < 32, "use sum32"); return __int_as_float(__builtin_amdgcn_ds_swizzle(__float_as_int(v), (K << 10) | 0x1f)); }
; template <class TIn, class TOut, int ost, bool HAS_SS>
; __device__ __forceinline__ void causal_swa_block(const BlockRef<TIn, TOut>& cur_, const BlockRef<TIn, TOut>& nxt_, int skv, int W, char* lds, Seam<TIn>& S, int cbl  ) {
;     ...
;     for (int r = 0; r < 16; ++r) { const unsigned rowoff = ob0 + (unsigned)(((r & 3) + 8 * (r >> 2)) * ost * 2); float ss_ = 0.f;
; #pragma unroll
;         for (int d0 = 0; d0 < 4; ++d0) { const float v = o[d0][r] * rli[r]; ss_ += v * v;
;             const float vn = shx<1>(v);
;             if ((r32e & 1) == 0) *(unsigned*)(Ob + rowoff + d0 * 64) = cvtpk(v, vn); }
;         if (HAS_SS) { ss_ += shx<1>(ss_); ss_ += shx<2>(ss_); ss_ += shx<4>(ss_); ss_ += shx<8>(ss_); ss_ += shx<16>(ss_);
;             if (r32e == 0) *(float*)((char*)cur.SS + (unsigned)(wid * QBLK + 4 * hie + (r & 3) + 8 * (r >> 2)) * 32u) = ss_; }
.LBB0_1082:
	s_or_b64 exec, exec, s[12:13]
	v_mul_f32_e32 v0, v0, v0
	v_fmac_f32_e32 v0, v5, v5
	v_fmac_f32_e32 v0, v7, v7
	v_fmac_f32_e32 v0, v6, v6
	s_nop 1
	v_mov_b32_dpp v2, v0 quad_perm:[1,0,3,2] row_mask:0xf bank_mask:0xf
	s_waitcnt lgkmcnt(0)
	v_add_f32_e32 v0, v0, v2
	s_nop 1
	v_mov_b32_dpp v2, v0 quad_perm:[2,3,0,1] row_mask:0xf bank_mask:0xf
	s_waitcnt lgkmcnt(0)
	v_add_f32_e32 v0, v0, v2
	s_nop 1
	v_mov_b32_dpp v2, v0 quad_perm:[3,2,1,0] row_mask:0xf bank_mask:0xf
	s_nop 1
	v_mov_b32_dpp v2, v2 row_half_mirror row_mask:0xf bank_mask:0xf
	s_waitcnt lgkmcnt(0)
	v_add_f32_e32 v0, v0, v2
	s_nop 1
	v_mov_b32_dpp v2, v0 row_half_mirror row_mask:0xf bank_mask:0xf
	s_nop 1
	v_mov_b32_dpp v2, v2 row_mirror row_mask:0xf bank_mask:0xf
	s_waitcnt lgkmcnt(0)
	v_add_f32_e32 v0, v0, v2
	ds_swizzle_b32 v2, v0 offset:swizzle(SWAP,16)
	s_and_saveexec_b64 s[12:13], s[34:35]
	s_cbranch_execz .LBB0_882
	s_waitcnt lgkmcnt(0)
	v_add_f32_e32 v5, v0, v2
	v_lshlrev_b32_e32 v0, 5, v4
	v_lshl_add_u64 v[2:3], s[86:87], 0, v[0:1]
	global_store_dword v[2:3], v5, off
	s_branch .LBB0_882

; template <int K> __device__ __forceinline__ float shx(float v) { static_assert(K < 32, "use sum32"); return __int_as_float(__builtin_amdgcn_ds_swizzle(__float_as_int(v), (K << 10) | 0x1f)); }
; __device__ __forceinline__ unsigned pk2(float lo, float hi) { return f2bf(lo) | (f2bf(hi) << 16); }
; __device__ __forceinline__ float bflo(unsigned w) { return __uint_as_float(w << 16); }
; __device__ __forceinline__ float bfhi(unsigned w) { return __uint_as_float(w & 0xffff0000u); }
; __global__ void __launch_bounds__(NTHR, LB2) hymba_fwd(Args a) {
;     ...
;       for (int L = P2B_FIRST; L < 256; L += P2B_STRIDE) { const int pm = L >> 3, nblk = L & 7, j = pm & 7, c8 = nblk * 128 + (tid & 15) * 8;
;         f32x4 hi0 = {0.f, 0.f, 0.f, 0.f}, hi1 = {0.f, 0.f, 0.f, 0.f};
;         for (int i = 0; i < j; ++i) { const float* eh = ENDH + (pm - j + i) * 1024 + c8; const float* ea = ENDA + (pm - j + i) * 1024 + c8;
;             hi0 = *(const f32x4*)ea * hi0 + *(const f32x4*)eh; hi1 = *(const f32x4*)(ea + 4) * hi1 + *(const f32x4*)(eh + 4); }
; #pragma unroll 2
;         for (int p = 0; p < 8; ++p) { const unsigned row = (unsigned)(pm * 256 + p * 32 + (tid >> 4)), o = (row * 1024u + c8) * 2u;
;             const v4u hw = __builtin_nontemporal_load((const v4u*)((const char*)HL + o)), aw = __builtin_nontemporal_load((const v4u*)((const char*)AC + o)), gw = __builtin_nontemporal_load((const v4u*)((const char*)GG + o));
;             const f32x4 y0 = ((f32x4){bflo(hw.x), bfhi(hw.x), bflo(hw.y), bfhi(hw.y)} + (f32x4){bflo(aw.x), bfhi(aw.x), bflo(aw.y), bfhi(aw.y)} * hi0) * (f32x4){bflo(gw.x), bfhi(gw.x), bflo(gw.y), bfhi(gw.y)};
;             const f32x4 y1 = ((f32x4){bflo(hw.z), bfhi(hw.z), bflo(hw.w), bfhi(hw.w)} + (f32x4){bflo(aw.z), bfhi(aw.z), bflo(aw.w), bfhi(aw.w)} * hi1) * (f32x4){bflo(gw.z), bfhi(gw.z), bflo(gw.w), bfhi(gw.w)};
;             float ss = (y0.x * y0.x + y0.y * y0.y) + (y0.z * y0.z + y0.w * y0.w) + (y1.x * y1.x + y1.y * y1.y) + (y1.z * y1.z + y1.w * y1.w);
;             v4u ow; ow.x = pk2(y0.x, y0.y); ow.y = pk2(y0.z, y0.w); ow.z = pk2(y1.x, y1.y); ow.w = pk2(y1.z, y1.w);
;             *(v4u*)((char*)MIX + ((size_t)row * 2048 + 1024 + c8) * 2) = ow;
;             ss += shx<1>(ss); ss += shx<2>(ss); ss += shx<4>(ss); ss += shx<8>(ss);
;             if ((tid & 15) == 0) SSQL[row * 8 + nblk] = ss; } } }
.LBB0_1145:
	s_waitcnt lgkmcnt(0)
	global_load_dwordx4 v[0:3], v23, s[26:27] nt
	global_load_dwordx4 v[24:27], v23, s[28:29] nt
	global_load_dwordx4 v[28:31], v23, s[20:21] nt
	s_mov_b32 s0, 0xf000000
	s_waitcnt vmcnt(0)
	v_lshlrev_b32_e32 v32, 16, v0
	v_and_b32_e32 v33, 0xffff0000, v0
	v_lshlrev_b32_e32 v0, 16, v1
	v_and_b32_e32 v1, 0xffff0000, v1
	v_lshlrev_b32_e32 v34, 16, v24
	v_and_b32_e32 v35, 0xffff0000, v24
	v_lshlrev_b32_e32 v24, 16, v25
	v_and_b32_e32 v25, 0xffff0000, v25
	v_pk_fma_f32 v[32:33], v[6:7], v[34:35], v[32:33]
	v_pk_fma_f32 v[0:1], v[8:9], v[24:25], v[0:1]
	v_lshlrev_b32_e32 v24, 16, v28
	v_and_b32_e32 v25, 0xffff0000, v28
	v_lshlrev_b32_e32 v28, 16, v29
	v_and_b32_e32 v29, 0xffff0000, v29
	v_pk_mul_f32 v[0:1], v[0:1], v[28:29]
	v_pk_mul_f32 v[28:29], v[32:33], v[24:25]
	v_lshlrev_b32_e32 v24, 16, v2
	v_and_b32_e32 v25, 0xffff0000, v2
	v_lshlrev_b32_e32 v2, 16, v3
	v_and_b32_e32 v3, 0xffff0000, v3
	v_lshlrev_b32_e32 v32, 16, v26
	v_and_b32_e32 v33, 0xffff0000, v26
	v_lshlrev_b32_e32 v26, 16, v27
	v_and_b32_e32 v27, 0xffff0000, v27
	v_pk_fma_f32 v[24:25], v[10:11], v[32:33], v[24:25]
	v_pk_fma_f32 v[2:3], v[12:13], v[26:27], v[2:3]
	v_lshlrev_b32_e32 v26, 16, v30
	v_and_b32_e32 v27, 0xffff0000, v30
	v_pk_mul_f32 v[26:27], v[24:25], v[26:27]
	v_mul_f32_e32 v24, v29, v29
	v_mul_f32_e32 v25, v1, v1
	v_fmac_f32_e32 v24, v28, v28
	v_fmac_f32_e32 v25, v0, v0
	v_lshlrev_b32_e32 v30, 16, v31
	v_and_b32_e32 v31, 0xffff0000, v31
	v_add_f32_e32 v24, v24, v25
	v_mul_f32_e32 v25, v27, v27
	v_pk_mul_f32 v[2:3], v[2:3], v[30:31]
	v_fmac_f32_e32 v25, v26, v26
	v_add_f32_e32 v24, v25, v24
	v_mul_f32_e32 v25, v3, v3
	v_fmac_f32_e32 v25, v2, v2
	v_add_f32_e32 v24, v25, v24
	v_and_b32_sdwa v25, v0, v21 dst_sel:DWORD dst_unused:UNUSED_PAD src0_sel:WORD_1 src1_sel:DWORD
	v_and_b32_sdwa v30, v28, v21 dst_sel:DWORD dst_unused:UNUSED_PAD src0_sel:WORD_1 src1_sel:DWORD
	v_add3_u32 v28, v28, v30, s4
	v_add3_u32 v0, v0, v25, s4
	v_and_b32_sdwa v25, v1, v21 dst_sel:DWORD dst_unused:UNUSED_PAD src0_sel:WORD_1 src1_sel:DWORD
	v_and_b32_sdwa v30, v29, v21 dst_sel:DWORD dst_unused:UNUSED_PAD src0_sel:WORD_1 src1_sel:DWORD
	v_add3_u32 v1, v1, v25, s4
	v_add3_u32 v25, v29, v30, s4
	v_and_b32_e32 v1, 0xffff0000, v1
	v_and_b32_e32 v25, 0xffff0000, v25
	v_or_b32_sdwa v1, v1, v0 dst_sel:DWORD dst_unused:UNUSED_PAD src0_sel:DWORD src1_sel:WORD_1
	v_or_b32_sdwa v0, v25, v28 dst_sel:DWORD dst_unused:UNUSED_PAD src0_sel:DWORD src1_sel:WORD_1
	v_and_b32_sdwa v25, v2, v21 dst_sel:DWORD dst_unused:UNUSED_PAD src0_sel:WORD_1 src1_sel:DWORD
	v_and_b32_sdwa v28, v26, v21 dst_sel:DWORD dst_unused:UNUSED_PAD src0_sel:WORD_1 src1_sel:DWORD
	v_add3_u32 v26, v26, v28, s4
	v_add3_u32 v2, v2, v25, s4
	v_and_b32_sdwa v25, v3, v21 dst_sel:DWORD dst_unused:UNUSED_PAD src0_sel:WORD_1 src1_sel:DWORD
	v_and_b32_sdwa v28, v27, v21 dst_sel:DWORD dst_unused:UNUSED_PAD src0_sel:WORD_1 src1_sel:DWORD
	v_add3_u32 v3, v3, v25, s4
	v_add3_u32 v25, v27, v28, s4
	v_and_b32_e32 v3, 0xffff0000, v3
	v_and_b32_e32 v25, 0xffff0000, v25
	v_or_b32_sdwa v3, v3, v2 dst_sel:DWORD dst_unused:UNUSED_PAD src0_sel:DWORD src1_sel:WORD_1
	v_or_b32_sdwa v2, v25, v26 dst_sel:DWORD dst_unused:UNUSED_PAD src0_sel:DWORD src1_sel:WORD_1
	v_lshlrev_b64 v[26:27], 12, v[4:5]
	v_lshl_add_u64 v[26:27], v[14:15], 0, v[26:27]
	v_add_co_u32_e32 v26, vcc, s0, v26
	s_nop 1
	v_addc_co_u32_e32 v27, vcc, 0, v27, vcc
	global_store_dwordx4 v[26:27], v[0:3], off offset:2048
	s_nop 1
	v_mov_b32_dpp v0, v24 quad_perm:[1,0,3,2] row_mask:0xf bank_mask:0xf
	s_waitcnt lgkmcnt(0)
	v_add_f32_e32 v0, v24, v0
	s_nop 1
	v_mov_b32_dpp v1, v0 quad_perm:[2,3,0,1] row_mask:0xf bank_mask:0xf
	s_waitcnt lgkmcnt(0)
	v_add_f32_e32 v0, v0, v1
	s_nop 1
	v_mov_b32_dpp v1, v0 quad_perm:[3,2,1,0] row_mask:0xf bank_mask:0xf
	s_nop 1
	v_mov_b32_dpp v1, v1 row_half_mirror row_mask:0xf bank_mask:0xf
	s_waitcnt lgkmcnt(0)
	v_add_f32_e32 v2, v0, v1
	s_nop 1
	v_mov_b32_dpp v3, v2 row_half_mirror row_mask:0xf bank_mask:0xf
	s_nop 1
	v_mov_b32_dpp v3, v3 row_mirror row_mask:0xf bank_mask:0xf
	v_add_u32_e32 v0, s7, v22
	s_and_saveexec_b64 s[0:1], s[34:35]
	s_cbranch_execz .LBB0_1147
	v_mov_b32_e32 v1, v5
	v_lshl_add_u64 v[24:25], v[0:1], 2, s[24:25]
	s_waitcnt lgkmcnt(0)
	v_add_f32_e32 v1, v2, v3
	global_store_dword v[24:25], v1, off
; template <int K> __device__ __forceinline__ float shx(float v) { static_assert(K < 32, "use sum32"); return __int_as_float(__builtin_amdgcn_ds_swizzle(__float_as_int(v), (K << 10) | 0x1f)); }
; __device__ __forceinline__ unsigned pk2(float lo, float hi) { return f2bf(lo) | (f2bf(hi) << 16); }
; __device__ __forceinline__ float bflo(unsigned w) { return __uint_as_float(w << 16); }
; __device__ __forceinline__ float bfhi(unsigned w) { return __uint_as_float(w & 0xffff0000u); }
; __global__ void __launch_bounds__(NTHR, LB2) hymba_fwd(Args a) {
;     ...
; #pragma unroll 2
;         for (int p = 0; p < 8; ++p) { const unsigned row = (unsigned)(pm * 256 + p * 32 + (tid >> 4)), o = (row * 1024u + c8) * 2u;
;             const v4u hw = __builtin_nontemporal_load((const v4u*)((const char*)HL + o)), aw = __builtin_nontemporal_load((const v4u*)((const char*)AC + o)), gw = __builtin_nontemporal_load((const v4u*)((const char*)GG + o));
;             const f32x4 y0 = ((f32x4){bflo(hw.x), bfhi(hw.x), bflo(hw.y), bfhi(hw.y)} + (f32x4){bflo(aw.x), bfhi(aw.x), bflo(aw.y), bfhi(aw.y)} * hi0) * (f32x4){bflo(gw.x), bfhi(gw.x), bflo(gw.y), bfhi(gw.y)};
;             const f32x4 y1 = ((f32x4){bflo(hw.z), bfhi(hw.z), bflo(hw.w), bfhi(hw.w)} + (f32x4){bflo(aw.z), bfhi(aw.z), bflo(aw.w), bfhi(aw.w)} * hi1) * (f32x4){bflo(gw.z), bfhi(gw.z), bflo(gw.w), bfhi(gw.w)};
;             float ss = (y0.x * y0.x + y0.y * y0.y) + (y0.z * y0.z + y0.w * y0.w) + (y1.x * y1.x + y1.y * y1.y) + (y1.z * y1.z + y1.w * y1.w);
;             v4u ow; ow.x = pk2(y0.x, y0.y); ow.y = pk2(y0.z, y0.w); ow.z = pk2(y1.x, y1.y); ow.w = pk2(y1.z, y1.w);
;             *(v4u*)((char*)MIX + ((size_t)row * 2048 + 1024 + c8) * 2) = ow;
;             ss += shx<1>(ss); ss += shx<2>(ss); ss += shx<4>(ss); ss += shx<8>(ss);
;             if ((tid & 15) == 0) SSQL[row * 8 + nblk] = ss; } } }
.LBB0_1147:
	s_or_b64 exec, exec, s[0:1]
	v_add_u32_e32 v1, 0x10000, v23
	global_load_dwordx4 v[24:27], v1, s[26:27] nt
	global_load_dwordx4 v[28:31], v1, s[28:29] nt
	global_load_dwordx4 v[32:35], v1, s[20:21] nt
	v_add_u32_e32 v2, 32, v4
	s_waitcnt vmcnt(2)
	v_lshlrev_b32_e32 v36, 16, v24
	v_and_b32_e32 v37, 0xffff0000, v24
	v_lshlrev_b32_e32 v24, 16, v25
	v_and_b32_e32 v25, 0xffff0000, v25
	s_waitcnt vmcnt(1)
	v_lshlrev_b32_e32 v38, 16, v28
	v_and_b32_e32 v39, 0xffff0000, v28
	v_lshlrev_b32_e32 v28, 16, v29
	v_and_b32_e32 v29, 0xffff0000, v29
	v_pk_fma_f32 v[36:37], v[6:7], v[38:39], v[36:37]
	v_pk_fma_f32 v[24:25], v[8:9], v[28:29], v[24:25]
	s_waitcnt vmcnt(0)
	v_lshlrev_b32_e32 v28, 16, v32
	v_and_b32_e32 v29, 0xffff0000, v32
	v_lshlrev_b32_e32 v32, 16, v33
	v_and_b32_e32 v33, 0xffff0000, v33
	v_pk_mul_f32 v[24:25], v[24:25], v[32:33]
	v_pk_mul_f32 v[28:29], v[36:37], v[28:29]
	v_lshlrev_b32_e32 v32, 16, v26
	v_and_b32_e32 v33, 0xffff0000, v26
	v_lshlrev_b32_e32 v26, 16, v27
	v_and_b32_e32 v27, 0xffff0000, v27
	v_lshlrev_b32_e32 v36, 16, v30
	v_and_b32_e32 v37, 0xffff0000, v30
	v_lshlrev_b32_e32 v30, 16, v31
	v_and_b32_e32 v31, 0xffff0000, v31
	v_pk_fma_f32 v[32:33], v[10:11], v[36:37], v[32:33]
	v_pk_fma_f32 v[26:27], v[12:13], v[30:31], v[26:27]
	v_lshlrev_b32_e32 v30, 16, v34
	v_and_b32_e32 v31, 0xffff0000, v34
	v_mul_f32_e32 v1, v29, v29
	s_waitcnt lgkmcnt(0)
	v_mul_f32_e32 v3, v25, v25
	v_pk_mul_f32 v[30:31], v[32:33], v[30:31]
	v_fmac_f32_e32 v1, v28, v28
	v_fmac_f32_e32 v3, v24, v24
	v_lshlrev_b32_e32 v34, 16, v35
	v_and_b32_e32 v35, 0xffff0000, v35
	v_add_f32_e32 v1, v1, v3
	v_mul_f32_e32 v3, v31, v31
	v_pk_mul_f32 v[26:27], v[26:27], v[34:35]
	v_fmac_f32_e32 v3, v30, v30
	v_add_f32_e32 v1, v3, v1
	v_mul_f32_e32 v3, v27, v27
	v_fmac_f32_e32 v3, v26, v26
	v_add_f32_e32 v1, v3, v1
	v_and_b32_sdwa v3, v24, v21 dst_sel:DWORD dst_unused:UNUSED_PAD src0_sel:WORD_1 src1_sel:DWORD
	v_and_b32_sdwa v32, v28, v21 dst_sel:DWORD dst_unused:UNUSED_PAD src0_sel:WORD_1 src1_sel:DWORD
	v_add3_u32 v3, v24, v3, s4
	v_and_b32_sdwa v24, v25, v21 dst_sel:DWORD dst_unused:UNUSED_PAD src0_sel:WORD_1 src1_sel:DWORD
	v_add3_u32 v28, v28, v32, s4
	v_and_b32_sdwa v32, v29, v21 dst_sel:DWORD dst_unused:UNUSED_PAD src0_sel:WORD_1 src1_sel:DWORD
	v_add3_u32 v24, v25, v24, s4
	v_add3_u32 v25, v29, v32, s4
	v_and_b32_e32 v24, 0xffff0000, v24
	v_and_b32_e32 v29, 0xffff0000, v25
	v_or_b32_sdwa v25, v24, v3 dst_sel:DWORD dst_unused:UNUSED_PAD src0_sel:DWORD src1_sel:WORD_1
	v_and_b32_sdwa v3, v26, v21 dst_sel:DWORD dst_unused:UNUSED_PAD src0_sel:WORD_1 src1_sel:DWORD
	v_add3_u32 v3, v26, v3, s4
	v_and_b32_sdwa v26, v27, v21 dst_sel:DWORD dst_unused:UNUSED_PAD src0_sel:WORD_1 src1_sel:DWORD
	v_or_b32_sdwa v24, v29, v28 dst_sel:DWORD dst_unused:UNUSED_PAD src0_sel:DWORD src1_sel:WORD_1
	v_and_b32_sdwa v29, v31, v21 dst_sel:DWORD dst_unused:UNUSED_PAD src0_sel:WORD_1 src1_sel:DWORD
	v_add3_u32 v26, v27, v26, s4
	v_add3_u32 v27, v31, v29, s4
	v_and_b32_e32 v26, 0xffff0000, v26
	v_and_b32_e32 v29, 0xffff0000, v27
	v_or_b32_sdwa v27, v26, v3 dst_sel:DWORD dst_unused:UNUSED_PAD src0_sel:DWORD src1_sel:WORD_1
	v_mov_b32_e32 v3, v5
	v_lshlrev_b64 v[2:3], 12, v[2:3]
	v_and_b32_sdwa v28, v30, v21 dst_sel:DWORD dst_unused:UNUSED_PAD src0_sel:WORD_1 src1_sel:DWORD
	v_lshl_add_u64 v[2:3], v[14:15], 0, v[2:3]
	v_add3_u32 v28, v30, v28, s4
	v_add_co_u32_e32 v2, vcc, 0xf000000, v2
	v_or_b32_sdwa v26, v29, v28 dst_sel:DWORD dst_unused:UNUSED_PAD src0_sel:DWORD src1_sel:WORD_1
	s_nop 0
	v_addc_co_u32_e32 v3, vcc, 0, v3, vcc
	global_store_dwordx4 v[2:3], v[24:27], off offset:2048
	s_nop 1
	v_mov_b32_dpp v2, v1 quad_perm:[1,0,3,2] row_mask:0xf bank_mask:0xf
	s_waitcnt lgkmcnt(0)
	v_add_f32_e32 v1, v1, v2
	s_nop 1
	v_mov_b32_dpp v2, v1 quad_perm:[2,3,0,1] row_mask:0xf bank_mask:0xf
	s_waitcnt lgkmcnt(0)
	v_add_f32_e32 v1, v1, v2
	s_nop 1
	v_mov_b32_dpp v2, v1 quad_perm:[3,2,1,0] row_mask:0xf bank_mask:0xf
	s_nop 1
	v_mov_b32_dpp v2, v2 row_half_mirror row_mask:0xf bank_mask:0xf
	s_waitcnt lgkmcnt(0)
	v_add_f32_e32 v1, v1, v2
	s_nop 1
	v_mov_b32_dpp v2, v1 row_half_mirror row_mask:0xf bank_mask:0xf
	s_nop 1
	v_mov_b32_dpp v2, v2 row_mirror row_mask:0xf bank_mask:0xf
	s_and_saveexec_b64 s[0:1], s[34:35]
	s_cbranch_execz .LBB0_1144
	v_add_u32_e32 v24, 0x100, v0
	v_mov_b32_e32 v25, v5
	v_lshl_add_u64 v[24:25], v[24:25], 2, s[24:25]
	s_waitcnt lgkmcnt(0)
	v_add_f32_e32 v0, v1, v2
	global_store_dword v[24:25], v0, off
	s_branch .LBB0_1144

;     __device__ __forceinline__ bool next(int i, Unit& u) const { if (i != 0) return false; u.pm = 0; u.pn = 0; return true; }
;     __device__ __forceinline__ bool next(int i, Unit& u) const { return S.next(i, u); }
;     __host__ __device__ bool next(int i, Unit& u) const {
;         const long L = (long)i * G + c; if (L >= nwg) return false;
;         int wgid = (int)L; { const int q = nwg / NXCD, r = nwg % NXCD, xcd = wgid % NXCD, off = wgid / NXCD; wgid = (xcd < r ? xcd * (q + 1) : r * (q + 1) + (xcd - r) * q) + off; }
;         const int nig = WGM * nN, gid = wgid / nig, fm = gid * WGM, gsz = (nM - fm) < WGM ? (nM - fm) : WGM;
;         u.pm = fm + ((wgid % nig) % gsz); u.pn = (wgid % nig) / gsz; return true;
;     }
; template <class Epi, class Sched, bool ALIGN_EPI = false, bool SP2 = false>
; __device__ __forceinline__ void gemm_phase(PG8_LAS unsigned char* lds, const Gemm g, const Sched& S, const Epi& E) {
;     ...
;         const bool has_next = S.next(ui + 1, nxt);
;         const char* nA = has_next ? (const char*)g.A + (size_t)nxt.pm * tstepA : cA; const char* nB = has_next ? (const char*)g.Bt + (size_t)nxt.pn * tstepB : cB;
.LBB0_1821:
	s_add_i32 s57, s57, 1
	s_mul_i32 s21, s57, s11
	s_mul_hi_u32 s23, s57, s10
	s_add_i32 s23, s23, s21
	s_mul_i32 s21, s57, s10
	s_add_u32 s26, s21, s72
	s_addc_u32 s27, s23, s73
	s_cmp_eq_u32 s10, 0x100
	s_cbranch_scc0 .Lp7_noadj
	s_cmp_eq_u32 s57, 5
	s_cbranch_scc0 .Lp7_noadj
	s_cmp_lt_u32 s72, 128
	s_cbranch_scc1 .Lp7_noadj
	s_sub_u32 s26, s26, 128
	s_subb_u32 s27, s27, 0

; #define PG8_STAGE(bufoff, gbase, voff) do { _Pragma("unroll") for (int _i = 0; _i < 2; ++_i) \
;         __builtin_amdgcn_global_load_lds((const unsigned*)((const char*)(gbase) + (voff)[_i]), (PG8_LAS unsigned*)(lds + (bufoff) + ldsw + _i * 8192), 16, 0, 0); } while (0)
; #define PG8_LDA(dst, b, h) do { _Pragma("unroll") for (int m = 0; m < 4; ++m) _Pragma("unroll") for (int k = 0; k < 2; ++k) dst[m][k] = *(const PG8_LAS bf16x8*)(lds + PG8_SA(b, h) + aoff + m * 2048 + k * 1024); } while (0)
; #define PG8_LDB(dst, b, h) do { _Pragma("unroll") for (int n = 0; n < 2; ++n) _Pragma("unroll") for (int k = 0; k < 2; ++k) dst[n][k] = *(const PG8_LAS bf16x8*)(lds + PG8_SB(b, h) + boff + n * 2048 + k * 1024); } while (0)
; #define PG8_MMA(ai, bj, At, Bt) do { __builtin_amdgcn_s_setprio(1); _Pragma("unroll") for (int m = 0; m < 4; ++m) _Pragma("unroll") for (int n = 0; n < 2; ++n) _Pragma("unroll") for (int k = 0; k < 2; ++k) \
;         acc[ai][bj][m][n] = __builtin_amdgcn_mfma_f32_16x16x32_bf16(Bt[n][k], At[m][k], acc[ai][bj][m][n], 0, 0, 0); __builtin_amdgcn_s_setprio(0); } while (0)
; template <class Epi, class Sched, bool ALIGN_EPI = false, bool SP2 = false>
; __device__ __forceinline__ void gemm_phase(PG8_LAS unsigned char* lds, const Gemm g, const Sched& S, const Epi& E) {
;     ...
;         for (int t = 0; t < nt; t += 2) {
;             const bool last = (t == nt - 2);
;             if constexpr (Epi::HAS_MID) { if (t == E.mid_t) E.mid(acc, cur, wr, wc, fr, fq); }
;             const char* a1 = cA + (size_t)(t + 1) * kstep;
;             const char* a2 = last ? nA : cA + (size_t)(t + 2) * kstep; const char* b2 = last ? nB : cB + (size_t)(t + 2) * kstep;
;             const char* a3 = a2 + kstep; const char* b3 = b2 + kstep;
;             if (last && has_next) S.a_ready(nxt);
;             if constexpr (SP2) {
;             PG8_LDB(B0, 0, 0); PG8_LDB(B1, 0, 1); PG8_SCHED; PG8_LDA(At, 0, 0); PG8_STAGE(PG8_SA(1, 1), a1 + hstepA, voffA);
;             PG8_WAIT_V(8); PG8_WAIT_L(0); PG8_BAR; PG8_MMA(0, 0, At, B0); PG8_MMA(0, 1, At, B1); PG8_BAR; PG8_SCHED;
;     ...
;         for (int a = 0; a < 2; ++a)
; #pragma unroll
;             for (int b = 0; b < 2; ++b)
; #pragma unroll
;                 for (int m = 0; m < 4; ++m)
; #pragma unroll
;                     for (int n = 0; n < 2; ++n) acc[a][b][m][n] = (f32x4){0.f, 0.f, 0.f, 0.f};
;         cur = nxt; cA = nA; cB = nB; ++ui;
.LBB0_1823:
	s_ashr_i32 s25, s24, 31
	s_lshl_b64 s[26:27], s[24:25], 20
	s_add_u32 s26, s48, s26
	s_addc_u32 s27, s49, s27
	s_and_b64 s[28:29], s[36:37], exec
	s_cselect_b32 s21, s27, s31
	s_cselect_b32 s25, s26, s30
	s_ashr_i32 s23, s22, 31
	s_lshl_b64 s[28:29], s[22:23], 20
	s_add_u32 s28, s90, s28
	s_addc_u32 s29, s91, s29
	s_and_b64 s[38:39], s[36:37], exec
	s_cselect_b32 s23, s29, s35
	s_cselect_b32 s59, s28, s34
	s_add_u32 s30, s30, 0x80080
	s_addc_u32 s31, s31, 0
	s_add_u32 s60, s34, 0x100
	v_mov_b32_e32 v0, 0
	s_addc_u32 s61, s35, 0
	s_mov_b32 s62, -2
	v_mov_b32_e32 v1, v0
	v_mov_b32_e32 v2, v0
	v_mov_b32_e32 v3, v0
	v_mov_b32_e32 v8, v0
	v_mov_b32_e32 v9, v0
	v_mov_b32_e32 v10, v0
	v_mov_b32_e32 v11, v0
	v_mov_b32_e32 v16, v0
	v_mov_b32_e32 v17, v0
	v_mov_b32_e32 v18, v0
	v_mov_b32_e32 v19, v0
	v_mov_b32_e32 v24, v0
	v_mov_b32_e32 v25, v0
	v_mov_b32_e32 v26, v0
	v_mov_b32_e32 v27, v0
	v_mov_b32_e32 v32, v0
	v_mov_b32_e32 v33, v0
	v_mov_b32_e32 v34, v0
	v_mov_b32_e32 v35, v0
	v_mov_b32_e32 v40, v0
	v_mov_b32_e32 v41, v0
	v_mov_b32_e32 v42, v0
	v_mov_b32_e32 v43, v0
	v_mov_b32_e32 v48, v0
	v_mov_b32_e32 v49, v0
	v_mov_b32_e32 v50, v0
	v_mov_b32_e32 v51, v0
	v_mov_b32_e32 v56, v0
	v_mov_b32_e32 v57, v0
	v_mov_b32_e32 v58, v0
	v_mov_b32_e32 v59, v0
	v_mov_b32_e32 v4, v0
	v_mov_b32_e32 v5, v0
	v_mov_b32_e32 v6, v0
	v_mov_b32_e32 v7, v0
	v_mov_b32_e32 v12, v0
	v_mov_b32_e32 v13, v0
	v_mov_b32_e32 v14, v0
	v_mov_b32_e32 v15, v0
	v_mov_b32_e32 v20, v0
	v_mov_b32_e32 v21, v0
	v_mov_b32_e32 v22, v0
	v_mov_b32_e32 v23, v0
	v_mov_b32_e32 v28, v0
	v_mov_b32_e32 v29, v0
	v_mov_b32_e32 v30, v0
	v_mov_b32_e32 v31, v0
	v_mov_b32_e32 v36, v0
	v_mov_b32_e32 v37, v0
	v_mov_b32_e32 v38, v0
	v_mov_b32_e32 v39, v0
	v_mov_b32_e32 v44, v0
	v_mov_b32_e32 v45, v0
	v_mov_b32_e32 v46, v0
	v_mov_b32_e32 v47, v0
	v_mov_b32_e32 v52, v0
	v_mov_b32_e32 v53, v0
	v_mov_b32_e32 v54, v0
	v_mov_b32_e32 v55, v0
	v_mov_b32_e32 v60, v0
	v_mov_b32_e32 v61, v0
	v_mov_b32_e32 v62, v0
	v_mov_b32_e32 v63, v0
	v_mov_b32_e32 v64, v0
	v_mov_b32_e32 v65, v0
	v_mov_b32_e32 v66, v0
	v_mov_b32_e32 v67, v0
	v_mov_b32_e32 v72, v0
	v_mov_b32_e32 v73, v0
	v_mov_b32_e32 v74, v0
	v_mov_b32_e32 v75, v0
	v_mov_b32_e32 v80, v0
	v_mov_b32_e32 v81, v0
	v_mov_b32_e32 v82, v0
	v_mov_b32_e32 v83, v0
	v_mov_b32_e32 v88, v0
	v_mov_b32_e32 v89, v0
	v_mov_b32_e32 v90, v0
	v_mov_b32_e32 v91, v0
	v_mov_b32_e32 v96, v0
	v_mov_b32_e32 v97, v0
	v_mov_b32_e32 v98, v0
	v_mov_b32_e32 v99, v0
	v_mov_b32_e32 v104, v0
	v_mov_b32_e32 v105, v0
	v_mov_b32_e32 v106, v0
	v_mov_b32_e32 v107, v0
	v_mov_b32_e32 v112, v0
	v_mov_b32_e32 v113, v0
	v_mov_b32_e32 v114, v0
	v_mov_b32_e32 v115, v0
	v_mov_b32_e32 v120, v0
	v_mov_b32_e32 v121, v0
	v_mov_b32_e32 v122, v0
	v_mov_b32_e32 v123, v0
	v_mov_b32_e32 v68, v0
	v_mov_b32_e32 v69, v0
	v_mov_b32_e32 v70, v0
	v_mov_b32_e32 v71, v0
	v_mov_b32_e32 v76, v0
	v_mov_b32_e32 v77, v0
	v_mov_b32_e32 v78, v0
	v_mov_b32_e32 v79, v0
	v_mov_b32_e32 v84, v0
	v_mov_b32_e32 v85, v0
	v_mov_b32_e32 v86, v0
	v_mov_b32_e32 v87, v0
	v_mov_b32_e32 v92, v0
	v_mov_b32_e32 v93, v0
	v_mov_b32_e32 v94, v0
	v_mov_b32_e32 v95, v0
	v_mov_b32_e32 v100, v0
	v_mov_b32_e32 v101, v0
	v_mov_b32_e32 v102, v0
	v_mov_b32_e32 v103, v0
	v_mov_b32_e32 v108, v0
	v_mov_b32_e32 v109, v0
	v_mov_b32_e32 v110, v0
	v_mov_b32_e32 v111, v0
	v_mov_b32_e32 v116, v0
	v_mov_b32_e32 v117, v0
	v_mov_b32_e32 v118, v0
	v_mov_b32_e32 v119, v0
	v_mov_b32_e32 v124, v0
	v_mov_b32_e32 v125, v0
	v_mov_b32_e32 v126, v0
	v_mov_b32_e32 v127, v0
	s_cmp_eq_u32 s57, 6
	s_cbranch_scc0 .Lp7_full_loop
	s_cmp_eq_u32 s10, 0x100
	s_cbranch_scc1 .Lp7_half_dispatch
.Lp7_full_loop:
.LBB0_1824:
	ds_read_b128 v[144:147], v151
	ds_read_b128 v[156:159], v151 offset:1024
	ds_read_b128 v[160:163], v151 offset:2048
	ds_read_b128 v[164:167], v151 offset:3072
	ds_read_b128 v[168:171], v152
	ds_read_b128 v[172:175], v152 offset:1024
	ds_read_b128 v[176:179], v152 offset:2048
	ds_read_b128 v[180:183], v152 offset:3072
	s_add_u32 s34, s30, 0xfff80080
	s_addc_u32 s35, s31, -1
	s_cmp_eq_u32 s62, 28
	s_cselect_b32 s39, s21, s35
	s_cselect_b32 s38, s25, s34
	s_cselect_b32 s35, s23, s61
	s_cselect_b32 s34, s59, s60
	v_lshl_add_u64 v[216:217], s[30:31], 0, v[136:137]
	s_add_i32 m0, s6, 0xc000
	ds_read_b128 v[184:187], v153
	ds_read_b128 v[188:191], v153 offset:1024
	ds_read_b128 v[192:195], v153 offset:2048
	ds_read_b128 v[196:199], v153 offset:3072
	ds_read_b128 v[200:203], v153 offset:4096
	ds_read_b128 v[204:207], v153 offset:5120
	ds_read_b128 v[208:211], v153 offset:6144
	ds_read_b128 v[212:215], v153 offset:7168
	global_load_lds_dwordx4 v[216:217], off
	v_lshl_add_u64 v[216:217], s[30:31], 0, v[138:139]
	s_add_i32 m0, s6, 0xe000
	s_nop 0
	global_load_lds_dwordx4 v[216:217], off
	s_waitcnt vmcnt(8)
	s_waitcnt lgkmcnt(0)
	s_barrier
; #define PG8_STAGE(bufoff, gbase, voff) do { _Pragma("unroll") for (int _i = 0; _i < 2; ++_i) \
;         __builtin_amdgcn_global_load_lds((const unsigned*)((const char*)(gbase) + (voff)[_i]), (PG8_LAS unsigned*)(lds + (bufoff) + ldsw + _i * 8192), 16, 0, 0); } while (0)
; #define PG8_LDA(dst, b, h) do { _Pragma("unroll") for (int m = 0; m < 4; ++m) _Pragma("unroll") for (int k = 0; k < 2; ++k) dst[m][k] = *(const PG8_LAS bf16x8*)(lds + PG8_SA(b, h) + aoff + m * 2048 + k * 1024); } while (0)
; #define PG8_MMA(ai, bj, At, Bt) do { __builtin_amdgcn_s_setprio(1); _Pragma("unroll") for (int m = 0; m < 4; ++m) _Pragma("unroll") for (int n = 0; n < 2; ++n) _Pragma("unroll") for (int k = 0; k < 2; ++k) \
;         acc[ai][bj][m][n] = __builtin_amdgcn_mfma_f32_16x16x32_bf16(Bt[n][k], At[m][k], acc[ai][bj][m][n], 0, 0, 0); __builtin_amdgcn_s_setprio(0); } while (0)
; #define PG8_WAIT_V(n) asm volatile("s_waitcnt vmcnt(" #n ")" ::: "memory")
; #define PG8_WAIT_L(n) asm volatile("s_waitcnt lgkmcnt(" #n ")" ::: "memory")
; #define PG8_BAR __builtin_amdgcn_s_barrier()
; #define PG8_SCHED __builtin_amdgcn_sched_barrier(0)
; template <class Epi, class Sched, bool ALIGN_EPI = false, bool SP2 = false>
; __device__ __forceinline__ void gemm_phase(PG8_LAS unsigned char* lds, const Gemm g, const Sched& S, const Epi& E) {
;     ...
;             PG8_WAIT_V(8); PG8_WAIT_L(0); PG8_BAR; PG8_MMA(0, 0, At, B0); PG8_MMA(0, 1, At, B1); PG8_BAR; PG8_SCHED;
;             PG8_LDA(At, 0, 1); PG8_STAGE(PG8_SB(0, 0), b2, voffB); PG8_STAGE(PG8_SB(0, 1), b2 + hstepB, voffB); PG8_STAGE(PG8_SA(0, 0), a2, voffA);
;             PG8_WAIT_V(8); PG8_WAIT_L(0); PG8_BAR; PG8_MMA(1, 0, At, B0); PG8_MMA(1, 1, At, B1); PG8_BAR; PG8_SCHED;
	s_setprio 1
	s_waitcnt lgkmcnt(0)
	v_mfma_f32_16x16x32_bf16 v[124:127], v[144:147], v[184:187], v[124:127]
	v_mfma_f32_16x16x32_bf16 v[116:119], v[160:163], v[184:187], v[116:119]
	v_mfma_f32_16x16x32_bf16 v[108:111], v[144:147], v[192:195], v[108:111]
	v_mfma_f32_16x16x32_bf16 v[100:103], v[160:163], v[192:195], v[100:103]
	v_mfma_f32_16x16x32_bf16 v[92:95], v[144:147], v[200:203], v[92:95]
	v_mfma_f32_16x16x32_bf16 v[84:87], v[160:163], v[200:203], v[84:87]
	v_mfma_f32_16x16x32_bf16 v[76:79], v[144:147], v[208:211], v[76:79]
	v_mfma_f32_16x16x32_bf16 v[68:71], v[160:163], v[208:211], v[68:71]
	v_mfma_f32_16x16x32_bf16 v[124:127], v[156:159], v[188:191], v[124:127]
	v_mfma_f32_16x16x32_bf16 v[116:119], v[164:167], v[188:191], v[116:119]
	v_mfma_f32_16x16x32_bf16 v[108:111], v[156:159], v[196:199], v[108:111]
	v_mfma_f32_16x16x32_bf16 v[100:103], v[164:167], v[196:199], v[100:103]
	v_mfma_f32_16x16x32_bf16 v[92:95], v[156:159], v[204:207], v[92:95]
	v_mfma_f32_16x16x32_bf16 v[84:87], v[164:167], v[204:207], v[84:87]
	v_mfma_f32_16x16x32_bf16 v[76:79], v[156:159], v[212:215], v[76:79]
	v_mfma_f32_16x16x32_bf16 v[68:71], v[164:167], v[212:215], v[68:71]
	s_setprio 0
	s_setprio 1
	v_mfma_f32_16x16x32_bf16 v[120:123], v[168:171], v[184:187], v[120:123]
	v_mfma_f32_16x16x32_bf16 v[112:115], v[176:179], v[184:187], v[112:115]
	v_mfma_f32_16x16x32_bf16 v[104:107], v[168:171], v[192:195], v[104:107]
	v_mfma_f32_16x16x32_bf16 v[96:99], v[176:179], v[192:195], v[96:99]
	v_mfma_f32_16x16x32_bf16 v[88:91], v[168:171], v[200:203], v[88:91]
	v_mfma_f32_16x16x32_bf16 v[80:83], v[176:179], v[200:203], v[80:83]
	v_mfma_f32_16x16x32_bf16 v[72:75], v[168:171], v[208:211], v[72:75]
	v_mfma_f32_16x16x32_bf16 v[64:67], v[176:179], v[208:211], v[64:67]
	v_mfma_f32_16x16x32_bf16 v[120:123], v[172:175], v[188:191], v[120:123]
	v_mfma_f32_16x16x32_bf16 v[112:115], v[180:183], v[188:191], v[112:115]
	v_mfma_f32_16x16x32_bf16 v[104:107], v[172:175], v[196:199], v[104:107]
	v_mfma_f32_16x16x32_bf16 v[96:99], v[180:183], v[196:199], v[96:99]
	v_mfma_f32_16x16x32_bf16 v[88:91], v[172:175], v[204:207], v[88:91]
	v_mfma_f32_16x16x32_bf16 v[80:83], v[180:183], v[204:207], v[80:83]
	v_mfma_f32_16x16x32_bf16 v[72:75], v[172:175], v[212:215], v[72:75]
	v_mfma_f32_16x16x32_bf16 v[64:67], v[180:183], v[212:215], v[64:67]
	s_setprio 0
	s_barrier
	s_add_i32 s63, s53, s4
	v_lshl_add_u64 v[216:217], s[34:35], 0, v[132:133]
	s_mov_b32 m0, s63
	ds_read_b128 v[184:187], v153 offset:16384
	ds_read_b128 v[188:191], v153 offset:17408
	ds_read_b128 v[192:195], v153 offset:18432
	ds_read_b128 v[196:199], v153 offset:19456
	ds_read_b128 v[200:203], v153 offset:20480
	ds_read_b128 v[204:207], v153 offset:21504
	ds_read_b128 v[208:211], v153 offset:22528
	ds_read_b128 v[212:215], v153 offset:23552
	global_load_lds_dwordx4 v[216:217], off
	s_add_i32 m0, s63, 0x2000
	s_add_u32 s64, s34, 0x80000
	v_lshl_add_u64 v[218:219], s[34:35], 0, v[128:129]
	s_addc_u32 s65, s35, 0
	s_add_i32 s63, s54, s4
	global_load_lds_dwordx4 v[218:219], off
	v_lshl_add_u64 v[220:221], s[64:65], 0, v[132:133]
	s_mov_b32 m0, s63
	v_lshl_add_u64 v[222:223], s[38:39], 0, v[130:131]
	global_load_lds_dwordx4 v[220:221], off
	v_lshl_add_u64 v[220:221], s[64:65], 0, v[128:129]
	s_add_i32 m0, s63, 0x2000
	s_nop 0
	global_load_lds_dwordx4 v[220:221], off
	v_lshl_add_u64 v[220:221], s[38:39], 0, v[134:135]
	s_mov_b32 m0, s6
	s_nop 0
	global_load_lds_dwordx4 v[220:221], off
	s_mov_b32 m0, s7
	s_nop 0
	global_load_lds_dwordx4 v[222:223], off
	s_waitcnt vmcnt(8)
	s_waitcnt lgkmcnt(0)
	s_barrier
	s_setprio 1
	s_waitcnt lgkmcnt(0)
	v_mfma_f32_16x16x32_bf16 v[60:63], v[144:147], v[184:187], v[60:63]
	v_mfma_f32_16x16x32_bf16 v[52:55], v[160:163], v[184:187], v[52:55]
	v_mfma_f32_16x16x32_bf16 v[44:47], v[144:147], v[192:195], v[44:47]
	v_mfma_f32_16x16x32_bf16 v[36:39], v[160:163], v[192:195], v[36:39]
	v_mfma_f32_16x16x32_bf16 v[28:31], v[144:147], v[200:203], v[28:31]
	v_mfma_f32_16x16x32_bf16 v[20:23], v[160:163], v[200:203], v[20:23]
	v_mfma_f32_16x16x32_bf16 v[12:15], v[144:147], v[208:211], v[12:15]
	v_mfma_f32_16x16x32_bf16 v[4:7], v[160:163], v[208:211], v[4:7]
	v_mfma_f32_16x16x32_bf16 v[60:63], v[156:159], v[188:191], v[60:63]
	v_mfma_f32_16x16x32_bf16 v[52:55], v[164:167], v[188:191], v[52:55]
	v_mfma_f32_16x16x32_bf16 v[44:47], v[156:159], v[196:199], v[44:47]
	v_mfma_f32_16x16x32_bf16 v[36:39], v[164:167], v[196:199], v[36:39]
	v_mfma_f32_16x16x32_bf16 v[28:31], v[156:159], v[204:207], v[28:31]
	v_mfma_f32_16x16x32_bf16 v[20:23], v[164:167], v[204:207], v[20:23]
	v_mfma_f32_16x16x32_bf16 v[12:15], v[156:159], v[212:215], v[12:15]
	v_mfma_f32_16x16x32_bf16 v[4:7], v[164:167], v[212:215], v[4:7]
	s_setprio 0
	s_setprio 1
	v_mfma_f32_16x16x32_bf16 v[56:59], v[168:171], v[184:187], v[56:59]
	v_mfma_f32_16x16x32_bf16 v[48:51], v[176:179], v[184:187], v[48:51]
	v_mfma_f32_16x16x32_bf16 v[40:43], v[168:171], v[192:195], v[40:43]
	v_mfma_f32_16x16x32_bf16 v[32:35], v[176:179], v[192:195], v[32:35]
	v_mfma_f32_16x16x32_bf16 v[24:27], v[168:171], v[200:203], v[24:27]
	v_mfma_f32_16x16x32_bf16 v[16:19], v[176:179], v[200:203], v[16:19]
	v_mfma_f32_16x16x32_bf16 v[8:11], v[168:171], v[208:211], v[8:11]
	v_mfma_f32_16x16x32_bf16 v[0:3], v[176:179], v[208:211], v[0:3]
	v_mfma_f32_16x16x32_bf16 v[56:59], v[172:175], v[188:191], v[56:59]
	v_mfma_f32_16x16x32_bf16 v[48:51], v[180:183], v[188:191], v[48:51]
	v_mfma_f32_16x16x32_bf16 v[40:43], v[172:175], v[196:199], v[40:43]
	v_mfma_f32_16x16x32_bf16 v[32:35], v[180:183], v[196:199], v[32:35]
	v_mfma_f32_16x16x32_bf16 v[24:27], v[172:175], v[204:207], v[24:27]
	v_mfma_f32_16x16x32_bf16 v[16:19], v[180:183], v[204:207], v[16:19]
	v_mfma_f32_16x16x32_bf16 v[8:11], v[172:175], v[212:215], v[8:11]
	v_mfma_f32_16x16x32_bf16 v[0:3], v[180:183], v[212:215], v[0:3]
	s_setprio 0
	s_barrier
; #define PG8_STAGE(bufoff, gbase, voff) do { _Pragma("unroll") for (int _i = 0; _i < 2; ++_i) \
;         __builtin_amdgcn_global_load_lds((const unsigned*)((const char*)(gbase) + (voff)[_i]), (PG8_LAS unsigned*)(lds + (bufoff) + ldsw + _i * 8192), 16, 0, 0); } while (0)
; #define PG8_LDA(dst, b, h) do { _Pragma("unroll") for (int m = 0; m < 4; ++m) _Pragma("unroll") for (int k = 0; k < 2; ++k) dst[m][k] = *(const PG8_LAS bf16x8*)(lds + PG8_SA(b, h) + aoff + m * 2048 + k * 1024); } while (0)
; #define PG8_LDB(dst, b, h) do { _Pragma("unroll") for (int n = 0; n < 2; ++n) _Pragma("unroll") for (int k = 0; k < 2; ++k) dst[n][k] = *(const PG8_LAS bf16x8*)(lds + PG8_SB(b, h) + boff + n * 2048 + k * 1024); } while (0)
; #define PG8_MMA(ai, bj, At, Bt) do { __builtin_amdgcn_s_setprio(1); _Pragma("unroll") for (int m = 0; m < 4; ++m) _Pragma("unroll") for (int n = 0; n < 2; ++n) _Pragma("unroll") for (int k = 0; k < 2; ++k) \
;         acc[ai][bj][m][n] = __builtin_amdgcn_mfma_f32_16x16x32_bf16(Bt[n][k], At[m][k], acc[ai][bj][m][n], 0, 0, 0); __builtin_amdgcn_s_setprio(0); } while (0)
; #define PG8_WAIT_V(n) asm volatile("s_waitcnt vmcnt(" #n ")" ::: "memory")
; #define PG8_WAIT_L(n) asm volatile("s_waitcnt lgkmcnt(" #n ")" ::: "memory")
; #define PG8_BAR __builtin_amdgcn_s_barrier()
; #define PG8_SCHED __builtin_amdgcn_sched_barrier(0)
; template <class Epi, class Sched, bool ALIGN_EPI = false, bool SP2 = false>
; __device__ __forceinline__ void gemm_phase(PG8_LAS unsigned char* lds, const Gemm g, const Sched& S, const Epi& E) {
;     ...
;             PG8_LDB(B0, 1, 0); PG8_LDB(B1, 1, 1); PG8_SCHED; PG8_LDA(At, 1, 0); PG8_STAGE(PG8_SA(0, 1), a2 + hstepA, voffA);
;             PG8_WAIT_V(8); PG8_WAIT_L(0); PG8_BAR; PG8_MMA(0, 0, At, B0); PG8_MMA(0, 1, At, B1); PG8_BAR; PG8_SCHED;
	s_add_i32 s63, 0, 0x18000
	v_add_u32_e32 v155, s63, v150
	s_add_i32 s64, 0, 0x1c000
	ds_read_b128 v[144:147], v155
	ds_read_b128 v[156:159], v155 offset:1024
	ds_read_b128 v[160:163], v155 offset:2048
	ds_read_b128 v[164:167], v155 offset:3072
	v_add_u32_e32 v155, s64, v150
	ds_read_b128 v[168:171], v155
	ds_read_b128 v[172:175], v155 offset:1024
	ds_read_b128 v[176:179], v155 offset:2048
	ds_read_b128 v[180:183], v155 offset:3072
	s_add_u32 s38, s38, 0x80000
	s_addc_u32 s39, s39, 0
	s_mov_b32 m0, s41
	v_lshl_add_u64 v[224:225], s[38:39], 0, v[134:135]
	ds_read_b128 v[184:187], v153 offset:32768
	ds_read_b128 v[188:191], v153 offset:33792
	ds_read_b128 v[192:195], v153 offset:34816
	ds_read_b128 v[196:199], v153 offset:35840
	ds_read_b128 v[200:203], v153 offset:36864
	ds_read_b128 v[204:207], v153 offset:37888
	ds_read_b128 v[208:211], v153 offset:38912
	ds_read_b128 v[212:215], v153 offset:39936
	global_load_lds_dwordx4 v[224:225], off
	v_lshl_add_u64 v[224:225], s[38:39], 0, v[130:131]
	s_mov_b32 m0, s42
	s_nop 0
	global_load_lds_dwordx4 v[224:225], off
	s_waitcnt vmcnt(8)
	s_waitcnt lgkmcnt(0)
	s_barrier
	s_setprio 1
	s_waitcnt lgkmcnt(0)
	v_mfma_f32_16x16x32_bf16 v[124:127], v[144:147], v[184:187], v[124:127]
	v_mfma_f32_16x16x32_bf16 v[116:119], v[160:163], v[184:187], v[116:119]
	v_mfma_f32_16x16x32_bf16 v[108:111], v[144:147], v[192:195], v[108:111]
	v_mfma_f32_16x16x32_bf16 v[100:103], v[160:163], v[192:195], v[100:103]
	v_mfma_f32_16x16x32_bf16 v[92:95], v[144:147], v[200:203], v[92:95]
	v_mfma_f32_16x16x32_bf16 v[84:87], v[160:163], v[200:203], v[84:87]
	v_mfma_f32_16x16x32_bf16 v[76:79], v[144:147], v[208:211], v[76:79]
	v_mfma_f32_16x16x32_bf16 v[68:71], v[160:163], v[208:211], v[68:71]
	v_mfma_f32_16x16x32_bf16 v[124:127], v[156:159], v[188:191], v[124:127]
	v_mfma_f32_16x16x32_bf16 v[116:119], v[164:167], v[188:191], v[116:119]
	v_mfma_f32_16x16x32_bf16 v[108:111], v[156:159], v[196:199], v[108:111]
	v_mfma_f32_16x16x32_bf16 v[100:103], v[164:167], v[196:199], v[100:103]
	v_mfma_f32_16x16x32_bf16 v[92:95], v[156:159], v[204:207], v[92:95]
	v_mfma_f32_16x16x32_bf16 v[84:87], v[164:167], v[204:207], v[84:87]
	v_mfma_f32_16x16x32_bf16 v[76:79], v[156:159], v[212:215], v[76:79]
	v_mfma_f32_16x16x32_bf16 v[68:71], v[164:167], v[212:215], v[68:71]
	s_setprio 0
	s_setprio 1
	v_mfma_f32_16x16x32_bf16 v[120:123], v[168:171], v[184:187], v[120:123]
	v_mfma_f32_16x16x32_bf16 v[112:115], v[176:179], v[184:187], v[112:115]
	v_mfma_f32_16x16x32_bf16 v[104:107], v[168:171], v[192:195], v[104:107]
	v_mfma_f32_16x16x32_bf16 v[96:99], v[176:179], v[192:195], v[96:99]
	v_mfma_f32_16x16x32_bf16 v[88:91], v[168:171], v[200:203], v[88:91]
	v_mfma_f32_16x16x32_bf16 v[80:83], v[176:179], v[200:203], v[80:83]
	v_mfma_f32_16x16x32_bf16 v[72:75], v[168:171], v[208:211], v[72:75]
	v_mfma_f32_16x16x32_bf16 v[64:67], v[176:179], v[208:211], v[64:67]
	v_mfma_f32_16x16x32_bf16 v[120:123], v[172:175], v[188:191], v[120:123]
	v_mfma_f32_16x16x32_bf16 v[112:115], v[180:183], v[188:191], v[112:115]
	v_mfma_f32_16x16x32_bf16 v[104:107], v[172:175], v[196:199], v[104:107]
	v_mfma_f32_16x16x32_bf16 v[96:99], v[180:183], v[196:199], v[96:99]
	v_mfma_f32_16x16x32_bf16 v[88:91], v[172:175], v[204:207], v[88:91]
	v_mfma_f32_16x16x32_bf16 v[80:83], v[180:183], v[204:207], v[80:83]
	v_mfma_f32_16x16x32_bf16 v[72:75], v[172:175], v[212:215], v[72:75]
	v_mfma_f32_16x16x32_bf16 v[64:67], v[180:183], v[212:215], v[64:67]
	s_setprio 0
	s_barrier
; #define PG8_STAGE(bufoff, gbase, voff) do { _Pragma("unroll") for (int _i = 0; _i < 2; ++_i) \
;         __builtin_amdgcn_global_load_lds((const unsigned*)((const char*)(gbase) + (voff)[_i]), (PG8_LAS unsigned*)(lds + (bufoff) + ldsw + _i * 8192), 16, 0, 0); } while (0)
; #define PG8_LDA(dst, b, h) do { _Pragma("unroll") for (int m = 0; m < 4; ++m) _Pragma("unroll") for (int k = 0; k < 2; ++k) dst[m][k] = *(const PG8_LAS bf16x8*)(lds + PG8_SA(b, h) + aoff + m * 2048 + k * 1024); } while (0)
; #define PG8_MMA(ai, bj, At, Bt) do { __builtin_amdgcn_s_setprio(1); _Pragma("unroll") for (int m = 0; m < 4; ++m) _Pragma("unroll") for (int n = 0; n < 2; ++n) _Pragma("unroll") for (int k = 0; k < 2; ++k) \
;         acc[ai][bj][m][n] = __builtin_amdgcn_mfma_f32_16x16x32_bf16(Bt[n][k], At[m][k], acc[ai][bj][m][n], 0, 0, 0); __builtin_amdgcn_s_setprio(0); } while (0)
; #define PG8_WAIT_V(n) asm volatile("s_waitcnt vmcnt(" #n ")" ::: "memory")
; #define PG8_WAIT_L(n) asm volatile("s_waitcnt lgkmcnt(" #n ")" ::: "memory")
; #define PG8_BAR __builtin_amdgcn_s_barrier()
; #define PG8_SCHED __builtin_amdgcn_sched_barrier(0)
; template <class Epi, class Sched, bool ALIGN_EPI = false, bool SP2 = false>
; __device__ __forceinline__ void gemm_phase(PG8_LAS unsigned char* lds, const Gemm g, const Sched& S, const Epi& E) {
;     ...
;         for (int t = 0; t < nt; t += 2) {
;     ...
;             PG8_LDA(At, 1, 1); PG8_STAGE(PG8_SB(1, 0), b3, voffB); PG8_STAGE(PG8_SB(1, 1), b3 + hstepB, voffB); PG8_STAGE(PG8_SA(1, 0), a3, voffA);
;             PG8_WAIT_V(8); PG8_WAIT_L(0); PG8_BAR; PG8_MMA(1, 0, At, B0); PG8_MMA(1, 1, At, B1); PG8_BAR; PG8_SCHED;
	s_add_i32 s38, s63, s4
	v_lshl_add_u64 v[216:217], v[216:217], 0, s[16:17]
	s_mov_b32 m0, s38
	ds_read_b128 v[184:187], v153 offset:49152
	ds_read_b128 v[188:191], v153 offset:50176
	ds_read_b128 v[192:195], v153 offset:51200
	ds_read_b128 v[196:199], v153 offset:52224
	ds_read_b128 v[200:203], v153 offset:53248
	ds_read_b128 v[204:207], v153 offset:54272
	ds_read_b128 v[208:211], v153 offset:55296
	ds_read_b128 v[212:215], v153 offset:56320
	global_load_lds_dwordx4 v[216:217], off
	s_add_i32 m0, s38, 0x2000
	s_add_u32 s34, s34, 0x80080
	v_lshl_add_u64 v[216:217], v[218:219], 0, s[16:17]
	s_addc_u32 s35, s35, 0
	s_add_i32 s38, s64, s4
	global_load_lds_dwordx4 v[216:217], off
	v_lshl_add_u64 v[216:217], s[34:35], 0, v[132:133]
	s_mov_b32 m0, s38
	s_nop 0
	global_load_lds_dwordx4 v[216:217], off
	v_lshl_add_u64 v[216:217], s[34:35], 0, v[128:129]
	s_add_i32 m0, s38, 0x2000
	s_nop 0
	global_load_lds_dwordx4 v[216:217], off
	v_lshl_add_u64 v[216:217], v[220:221], 0, s[16:17]
	s_mov_b32 m0, s46
	s_nop 0
	global_load_lds_dwordx4 v[216:217], off
	v_lshl_add_u64 v[216:217], v[222:223], 0, s[16:17]
	s_mov_b32 m0, s47
	s_nop 0
	global_load_lds_dwordx4 v[216:217], off
	s_waitcnt vmcnt(8)
	s_waitcnt lgkmcnt(0)
	s_barrier
	s_setprio 1
	s_waitcnt lgkmcnt(0)
	v_mfma_f32_16x16x32_bf16 v[60:63], v[144:147], v[184:187], v[60:63]
	v_mfma_f32_16x16x32_bf16 v[52:55], v[160:163], v[184:187], v[52:55]
	v_mfma_f32_16x16x32_bf16 v[44:47], v[144:147], v[192:195], v[44:47]
	v_mfma_f32_16x16x32_bf16 v[36:39], v[160:163], v[192:195], v[36:39]
	v_mfma_f32_16x16x32_bf16 v[28:31], v[144:147], v[200:203], v[28:31]
	v_mfma_f32_16x16x32_bf16 v[20:23], v[160:163], v[200:203], v[20:23]
	v_mfma_f32_16x16x32_bf16 v[12:15], v[144:147], v[208:211], v[12:15]
	v_mfma_f32_16x16x32_bf16 v[4:7], v[160:163], v[208:211], v[4:7]
	v_mfma_f32_16x16x32_bf16 v[60:63], v[156:159], v[188:191], v[60:63]
	v_mfma_f32_16x16x32_bf16 v[52:55], v[164:167], v[188:191], v[52:55]
	v_mfma_f32_16x16x32_bf16 v[44:47], v[156:159], v[196:199], v[44:47]
	v_mfma_f32_16x16x32_bf16 v[36:39], v[164:167], v[196:199], v[36:39]
	v_mfma_f32_16x16x32_bf16 v[28:31], v[156:159], v[204:207], v[28:31]
	v_mfma_f32_16x16x32_bf16 v[20:23], v[164:167], v[204:207], v[20:23]
	v_mfma_f32_16x16x32_bf16 v[12:15], v[156:159], v[212:215], v[12:15]
	v_mfma_f32_16x16x32_bf16 v[4:7], v[164:167], v[212:215], v[4:7]
	s_setprio 0
	s_setprio 1
	v_mfma_f32_16x16x32_bf16 v[56:59], v[168:171], v[184:187], v[56:59]
	v_mfma_f32_16x16x32_bf16 v[48:51], v[176:179], v[184:187], v[48:51]
	v_mfma_f32_16x16x32_bf16 v[40:43], v[168:171], v[192:195], v[40:43]
	v_mfma_f32_16x16x32_bf16 v[32:35], v[176:179], v[192:195], v[32:35]
	v_mfma_f32_16x16x32_bf16 v[24:27], v[168:171], v[200:203], v[24:27]
	v_mfma_f32_16x16x32_bf16 v[16:19], v[176:179], v[200:203], v[16:19]
	v_mfma_f32_16x16x32_bf16 v[8:11], v[168:171], v[208:211], v[8:11]
	v_mfma_f32_16x16x32_bf16 v[0:3], v[176:179], v[208:211], v[0:3]
	v_mfma_f32_16x16x32_bf16 v[56:59], v[172:175], v[188:191], v[56:59]
	v_mfma_f32_16x16x32_bf16 v[48:51], v[180:183], v[188:191], v[48:51]
	v_mfma_f32_16x16x32_bf16 v[40:43], v[172:175], v[196:199], v[40:43]
	v_mfma_f32_16x16x32_bf16 v[32:35], v[180:183], v[196:199], v[32:35]
	v_mfma_f32_16x16x32_bf16 v[24:27], v[172:175], v[204:207], v[24:27]
	v_mfma_f32_16x16x32_bf16 v[16:19], v[180:183], v[204:207], v[16:19]
	v_mfma_f32_16x16x32_bf16 v[8:11], v[172:175], v[212:215], v[8:11]
	v_mfma_f32_16x16x32_bf16 v[0:3], v[180:183], v[212:215], v[0:3]
	s_setprio 0
	s_barrier
	s_add_i32 s62, s62, 2
	s_add_u32 s30, s30, 0x100
	s_addc_u32 s31, s31, 0
	s_add_u32 s60, s60, 0x100
	s_addc_u32 s61, s61, 0
	s_cmp_gt_u32 s62, 29
	s_cbranch_scc0 .LBB0_1824

; __device__ __forceinline__ float sigmoidf_(float x) { return __builtin_amdgcn_rcpf(1.0f + __expf(-x)); }
; __device__ __forceinline__ u32x4 pack8(const f32x4& a, const f32x4& b) { u32x4 w; w.x = cvt_pk_bf16(a[0], a[1]); w.y = cvt_pk_bf16(a[2], a[3]); w.z = cvt_pk_bf16(b[0], b[1]); w.w = cvt_pk_bf16(b[2], b[3]); return w; }
;     __device__ __forceinline__ void operator()(const f32x4 (&acc)[2][2][4][2], const Unit& u, int wr, int wc, int fr, int fq) const {
;     ...
; #pragma unroll
;         for (int ai = 0; ai < 2; ++ai)
; #pragma unroll
;             for (int m = 0; m < 4; ++m) { const size_t row = (size_t)u.pm * BM + ai * HALF + wr * 64 + m * 16 + fr;
;                 const float rs = tab[ai * HALF + wr * 64 + m * 16 + fr];
;                 f32x4 h[2];
; #pragma unroll
;                 for (int n = 0; n < 2; ++n) { const f32x4 g = acc[ai][0][m][n] * rs, up = acc[ai][1][m][n] * rs;
; #pragma unroll
;                     for (int j = 0; j < 4; ++j) h[n][j] = g[j] * sigmoidf_(g[j]) * up[j]; }
;                 *(u32x4*)(H + row * 5632 + u.pn * HALF + wc * 32 + fq * 8) = pack8(h[0], h[1]); }
.LBB0_1833:
	s_ashr_i32 s21, s20, 31
	s_lshl_b64 s[20:21], s[20:21], 8
	s_add_u32 s20, s20, s43
	s_addc_u32 s21, s21, s51
	v_ashrrev_i32_e32 v145, 31, v144
	v_lshl_add_u32 v155, v144, 2, s52
	v_lshl_add_u64 v[146:147], s[20:21], 0, v[144:145]
	v_lshlrev_b32_e32 v144, 3, v156
	s_cmp_eq_u32 s57, 6
	s_cbranch_scc0 .Lp7_epi_full
	s_cmp_eq_u32 s10, 0x100
	s_cbranch_scc0 .Lp7_epi_full
	s_cmp_ge_u32 s72, 128
	s_cbranch_scc1 .Lp7_h1_epi
.Lp7_epi_full:
	ds_read_b32 v156, v155
	v_mov_b32_e32 v158, v120
	v_mov_b32_e32 v159, v124
	v_mov_b32_e32 v124, v121
	s_lshl_b32 s20, s58, 7
	s_waitcnt lgkmcnt(0)
	v_pk_mul_f32 v[158:159], v[158:159], v[156:157] op_sel_hi:[1,0]
	s_ashr_i32 s21, s20, 31
	v_mul_f32_e32 v120, 0xbfb8aa3b, v159
	v_exp_f32_e32 v120, v120
	v_ashrrev_i32_e32 v145, 31, v144
	v_add_f32_e32 v120, 1.0, v120
	v_rcp_f32_e32 v120, v120
	s_nop 0
	v_mul_f32_e32 v120, v159, v120
	v_mul_f32_e32 v157, v158, v120
	v_pk_mul_f32 v[120:121], v[124:125], v[156:157] op_sel_hi:[1,0]
	s_nop 0
	v_mul_f32_e32 v124, 0xbfb8aa3b, v121
	v_exp_f32_e32 v124, v124
	s_nop 0
	v_add_f32_e32 v124, 1.0, v124
	v_rcp_f32_e32 v124, v124
	s_nop 0
	v_mul_f32_e32 v121, v121, v124
	v_mul_f32_e32 v124, v120, v121
	v_mov_b32_e32 v120, v122
	v_mov_b32_e32 v121, v126
	v_pk_mul_f32 v[120:121], v[120:121], v[156:157] op_sel_hi:[1,0]
	v_mov_b32_e32 v126, v123
	v_mul_f32_e32 v122, 0xbfb8aa3b, v121
	v_exp_f32_e32 v122, v122
	s_nop 0
	v_add_f32_e32 v122, 1.0, v122
	v_rcp_f32_e32 v122, v122
	s_nop 0
	v_mul_f32_e32 v121, v121, v122
	v_mul_f32_e32 v122, v120, v121
	v_pk_mul_f32 v[120:121], v[126:127], v[156:157] op_sel_hi:[1,0]
	s_nop 0
	v_mul_f32_e32 v123, 0xbfb8aa3b, v121
	v_exp_f32_e32 v123, v123
	s_nop 0
	v_add_f32_e32 v123, 1.0, v123
	v_rcp_f32_e32 v123, v123
	s_nop 0
	v_mul_f32_e32 v121, v121, v123
	v_mul_f32_e32 v123, v120, v121
	v_mov_b32_e32 v120, v112
	v_mov_b32_e32 v121, v116
	v_pk_mul_f32 v[120:121], v[120:121], v[156:157] op_sel_hi:[1,0]
	v_mov_b32_e32 v116, v113
	v_mul_f32_e32 v112, 0xbfb8aa3b, v121
	v_exp_f32_e32 v112, v112
	s_nop 0
	v_add_f32_e32 v112, 1.0, v112
	v_rcp_f32_e32 v112, v112
	s_nop 0
	v_mul_f32_e32 v112, v121, v112
	v_mul_f32_e32 v120, v120, v112
	v_pk_mul_f32 v[112:113], v[116:117], v[156:157] op_sel_hi:[1,0]
	s_nop 0
	v_mul_f32_e32 v116, 0xbfb8aa3b, v113
	v_exp_f32_e32 v116, v116
	s_nop 0
	v_add_f32_e32 v116, 1.0, v116
	v_rcp_f32_e32 v116, v116
	s_nop 0
	v_mul_f32_e32 v113, v113, v116
	v_mul_f32_e32 v116, v112, v113
	v_mov_b32_e32 v112, v114
	v_mov_b32_e32 v113, v118
	v_pk_mul_f32 v[112:113], v[112:113], v[156:157] op_sel_hi:[1,0]
	v_mov_b32_e32 v118, v115
	v_mul_f32_e32 v114, 0xbfb8aa3b, v113
	v_exp_f32_e32 v114, v114
	s_nop 0
	v_add_f32_e32 v114, 1.0, v114
	v_rcp_f32_e32 v114, v114
	s_nop 0
	v_mul_f32_e32 v113, v113, v114
	v_mul_f32_e32 v117, v112, v113
	v_pk_mul_f32 v[112:113], v[118:119], v[156:157] op_sel_hi:[1,0]
	s_nop 0
	v_mul_f32_e32 v114, 0xbfb8aa3b, v113
	v_exp_f32_e32 v114, v114
	s_nop 0
	v_add_f32_e32 v114, 1.0, v114
	v_rcp_f32_e32 v114, v114
	s_nop 0
	v_mul_f32_e32 v113, v113, v114
	v_mul_f32_e32 v112, v112, v113
	v_cvt_pk_bf16_f32 v114, v157, v124
	v_cvt_pk_bf16_f32 v115, v122, v123
	v_cvt_pk_bf16_f32 v116, v120, v116
	v_cvt_pk_bf16_f32 v117, v117, v112
	v_mov_b64_e32 v[112:113], s[44:45]
	v_mad_u64_u32 v[112:113], s[30:31], v146, s56, v[112:113]
	v_mad_i32_i24 v113, v147, s56, v113
	v_lshl_add_u64 v[112:113], s[20:21], 1, v[112:113]
	v_lshl_add_u64 v[112:113], v[112:113], 0, s[12:13]
	v_lshl_add_u64 v[112:113], v[144:145], 1, v[112:113]
	global_store_dwordx4 v[112:113], v[114:117], off
	ds_read_b32 v114, v155 offset:64
	s_mov_b32 s20, 0x2c000
	v_mov_b32_e32 v116, v104
	v_mov_b32_e32 v117, v108
	v_mov_b32_e32 v108, v105
	s_waitcnt lgkmcnt(0)
	v_pk_mul_f32 v[116:117], v[116:117], v[114:115] op_sel_hi:[1,0]
	s_nop 0
	v_mul_f32_e32 v104, 0xbfb8aa3b, v117
	v_exp_f32_e32 v104, v104
	s_nop 0
	v_add_f32_e32 v104, 1.0, v104
	v_rcp_f32_e32 v104, v104
	s_nop 0
	v_mul_f32_e32 v104, v117, v104
	v_mul_f32_e32 v115, v116, v104
	v_pk_mul_f32 v[104:105], v[108:109], v[114:115] op_sel_hi:[1,0]
	s_nop 0
	v_mul_f32_e32 v108, 0xbfb8aa3b, v105
	v_exp_f32_e32 v108, v108
	s_nop 0
	v_add_f32_e32 v108, 1.0, v108
	v_rcp_f32_e32 v108, v108
	s_nop 0
	v_mul_f32_e32 v105, v105, v108
	v_mul_f32_e32 v108, v104, v105
	v_mov_b32_e32 v104, v106
	v_mov_b32_e32 v105, v110
	v_pk_mul_f32 v[104:105], v[104:105], v[114:115] op_sel_hi:[1,0]
	v_mov_b32_e32 v110, v107
	v_mul_f32_e32 v106, 0xbfb8aa3b, v105
	v_exp_f32_e32 v106, v106
	s_nop 0
	v_add_f32_e32 v106, 1.0, v106
	v_rcp_f32_e32 v106, v106
	s_nop 0
	v_mul_f32_e32 v105, v105, v106
	v_mul_f32_e32 v106, v104, v105
	v_pk_mul_f32 v[104:105], v[110:111], v[114:115] op_sel_hi:[1,0]
	s_nop 0
	v_mul_f32_e32 v107, 0xbfb8aa3b, v105
	v_exp_f32_e32 v107, v107
	s_nop 0
	v_add_f32_e32 v107, 1.0, v107
	v_rcp_f32_e32 v107, v107
	s_nop 0
	v_mul_f32_e32 v105, v105, v107
	v_mul_f32_e32 v107, v104, v105
	v_mov_b32_e32 v104, v96
	v_mov_b32_e32 v105, v100
	v_pk_mul_f32 v[104:105], v[104:105], v[114:115] op_sel_hi:[1,0]
	v_mov_b32_e32 v100, v97
	v_mul_f32_e32 v96, 0xbfb8aa3b, v105
	v_exp_f32_e32 v96, v96
	s_nop 0
	v_add_f32_e32 v96, 1.0, v96
	v_rcp_f32_e32 v96, v96
	s_nop 0
	v_mul_f32_e32 v96, v105, v96
	v_mul_f32_e32 v104, v104, v96
	v_pk_mul_f32 v[96:97], v[100:101], v[114:115] op_sel_hi:[1,0]
	s_nop 0
	v_mul_f32_e32 v100, 0xbfb8aa3b, v97
	v_exp_f32_e32 v100, v100
	s_nop 0
	v_add_f32_e32 v100, 1.0, v100
	v_rcp_f32_e32 v100, v100
	s_nop 0
	v_mul_f32_e32 v97, v97, v100
	v_mul_f32_e32 v100, v96, v97
	v_mov_b32_e32 v96, v98
	v_mov_b32_e32 v97, v102
	v_pk_mul_f32 v[96:97], v[96:97], v[114:115] op_sel_hi:[1,0]
	v_mov_b32_e32 v102, v99
	v_mul_f32_e32 v98, 0xbfb8aa3b, v97
	v_exp_f32_e32 v98, v98
	s_nop 0
	v_add_f32_e32 v98, 1.0, v98
	v_rcp_f32_e32 v98, v98
	s_nop 0
	v_mul_f32_e32 v97, v97, v98
	v_mul_f32_e32 v101, v96, v97
	v_pk_mul_f32 v[96:97], v[102:103], v[114:115] op_sel_hi:[1,0]
	s_nop 0
	v_mul_f32_e32 v98, 0xbfb8aa3b, v97
	v_exp_f32_e32 v98, v98
	s_nop 0
	v_add_f32_e32 v98, 1.0, v98
	v_rcp_f32_e32 v98, v98
	s_nop 0
	v_mul_f32_e32 v97, v97, v98
	v_mul_f32_e32 v99, v96, v97
	v_cvt_pk_bf16_f32 v96, v115, v108
	v_cvt_pk_bf16_f32 v97, v106, v107
	v_cvt_pk_bf16_f32 v98, v104, v100
	v_add_co_u32_e32 v100, vcc, s20, v112
	v_cvt_pk_bf16_f32 v99, v101, v99
	s_mov_b32 s20, 0x58000
	s_nop 0
	v_addc_co_u32_e32 v101, vcc, 0, v113, vcc
	global_store_dwordx4 v[100:101], v[96:99], off
	ds_read_b32 v96, v155 offset:128
	s_nop 0
	v_mov_b32_e32 v98, v88
	v_mov_b32_e32 v99, v92
	v_mov_b32_e32 v92, v89
	s_waitcnt lgkmcnt(0)
; __device__ __forceinline__ float sigmoidf_(float x) { return __builtin_amdgcn_rcpf(1.0f + __expf(-x)); }
; __device__ __forceinline__ u32x4 pack8(const f32x4& a, const f32x4& b) { u32x4 w; w.x = cvt_pk_bf16(a[0], a[1]); w.y = cvt_pk_bf16(a[2], a[3]); w.z = cvt_pk_bf16(b[0], b[1]); w.w = cvt_pk_bf16(b[2], b[3]); return w; }
;     __device__ __forceinline__ void operator()(const f32x4 (&acc)[2][2][4][2], const Unit& u, int wr, int wc, int fr, int fq) const {
;     ...
; #pragma unroll
;         for (int ai = 0; ai < 2; ++ai)
; #pragma unroll
;             for (int m = 0; m < 4; ++m) { const size_t row = (size_t)u.pm * BM + ai * HALF + wr * 64 + m * 16 + fr;
;                 const float rs = tab[ai * HALF + wr * 64 + m * 16 + fr];
;                 f32x4 h[2];
; #pragma unroll
;                 for (int n = 0; n < 2; ++n) { const f32x4 g = acc[ai][0][m][n] * rs, up = acc[ai][1][m][n] * rs;
; #pragma unroll
;                     for (int j = 0; j < 4; ++j) h[n][j] = g[j] * sigmoidf_(g[j]) * up[j]; }
;                 *(u32x4*)(H + row * 5632 + u.pn * HALF + wc * 32 + fq * 8) = pack8(h[0], h[1]); }
	v_pk_mul_f32 v[98:99], v[98:99], v[96:97] op_sel_hi:[1,0]
	s_nop 0
	v_mul_f32_e32 v88, 0xbfb8aa3b, v99
	v_exp_f32_e32 v88, v88
	s_nop 0
	v_add_f32_e32 v88, 1.0, v88
	v_rcp_f32_e32 v88, v88
	s_nop 0
	v_mul_f32_e32 v88, v99, v88
	v_mul_f32_e32 v97, v98, v88
	v_pk_mul_f32 v[88:89], v[92:93], v[96:97] op_sel_hi:[1,0]
	s_nop 0
	v_mul_f32_e32 v92, 0xbfb8aa3b, v89
	v_exp_f32_e32 v92, v92
	s_nop 0
	v_add_f32_e32 v92, 1.0, v92
	v_rcp_f32_e32 v92, v92
	s_nop 0
	v_mul_f32_e32 v89, v89, v92
	v_mul_f32_e32 v92, v88, v89
	v_mov_b32_e32 v88, v90
	v_mov_b32_e32 v89, v94
	v_pk_mul_f32 v[88:89], v[88:89], v[96:97] op_sel_hi:[1,0]
	v_mov_b32_e32 v94, v91
	v_mul_f32_e32 v90, 0xbfb8aa3b, v89
	v_exp_f32_e32 v90, v90
	s_nop 0
	v_add_f32_e32 v90, 1.0, v90
	v_rcp_f32_e32 v90, v90
	s_nop 0
	v_mul_f32_e32 v89, v89, v90
	v_mul_f32_e32 v90, v88, v89
	v_pk_mul_f32 v[88:89], v[94:95], v[96:97] op_sel_hi:[1,0]
	s_nop 0
	v_mul_f32_e32 v91, 0xbfb8aa3b, v89
	v_exp_f32_e32 v91, v91
	s_nop 0
	v_add_f32_e32 v91, 1.0, v91
	v_rcp_f32_e32 v91, v91
	s_nop 0
	v_mul_f32_e32 v89, v89, v91
	v_mul_f32_e32 v91, v88, v89
	v_mov_b32_e32 v88, v80
	v_mov_b32_e32 v89, v84
	v_pk_mul_f32 v[88:89], v[88:89], v[96:97] op_sel_hi:[1,0]
	v_mov_b32_e32 v84, v81
	v_mul_f32_e32 v80, 0xbfb8aa3b, v89
	v_exp_f32_e32 v80, v80
	s_nop 0
	v_add_f32_e32 v80, 1.0, v80
	v_rcp_f32_e32 v80, v80
	s_nop 0
	v_mul_f32_e32 v80, v89, v80
	v_mul_f32_e32 v88, v88, v80
	v_pk_mul_f32 v[80:81], v[84:85], v[96:97] op_sel_hi:[1,0]
	s_nop 0
	v_mul_f32_e32 v84, 0xbfb8aa3b, v81
	v_exp_f32_e32 v84, v84
	s_nop 0
	v_add_f32_e32 v84, 1.0, v84
	v_rcp_f32_e32 v84, v84
	s_nop 0
	v_mul_f32_e32 v81, v81, v84
	v_mul_f32_e32 v84, v80, v81
	v_mov_b32_e32 v80, v82
	v_mov_b32_e32 v81, v86
	v_pk_mul_f32 v[80:81], v[80:81], v[96:97] op_sel_hi:[1,0]
	v_mov_b32_e32 v86, v83
	v_mul_f32_e32 v82, 0xbfb8aa3b, v81
	v_exp_f32_e32 v82, v82
	s_nop 0
	v_add_f32_e32 v82, 1.0, v82
	v_rcp_f32_e32 v82, v82
	s_nop 0
	v_mul_f32_e32 v81, v81, v82
	v_mul_f32_e32 v85, v80, v81
	v_pk_mul_f32 v[80:81], v[86:87], v[96:97] op_sel_hi:[1,0]
	s_nop 0
	v_mul_f32_e32 v82, 0xbfb8aa3b, v81
	v_exp_f32_e32 v82, v82
	s_nop 0
	v_add_f32_e32 v82, 1.0, v82
	v_rcp_f32_e32 v82, v82
	s_nop 0
	v_mul_f32_e32 v81, v81, v82
	v_mul_f32_e32 v83, v80, v81
	v_cvt_pk_bf16_f32 v80, v97, v92
	v_cvt_pk_bf16_f32 v81, v90, v91
	v_cvt_pk_bf16_f32 v82, v88, v84
	v_add_co_u32_e32 v84, vcc, s20, v112
	v_cvt_pk_bf16_f32 v83, v85, v83
	s_mov_b32 s20, 0x84000
	s_nop 0
	v_addc_co_u32_e32 v85, vcc, 0, v113, vcc
	global_store_dwordx4 v[84:85], v[80:83], off
	ds_read_b32 v80, v155 offset:192
	s_nop 0
	v_mov_b32_e32 v82, v72
	v_mov_b32_e32 v83, v76
	v_mov_b32_e32 v76, v73
	s_waitcnt lgkmcnt(0)
	v_pk_mul_f32 v[82:83], v[82:83], v[80:81] op_sel_hi:[1,0]
	s_nop 0
	v_mul_f32_e32 v72, 0xbfb8aa3b, v83
	v_exp_f32_e32 v72, v72
	s_nop 0
	v_add_f32_e32 v72, 1.0, v72
	v_rcp_f32_e32 v72, v72
	s_nop 0
	v_mul_f32_e32 v72, v83, v72
	v_mul_f32_e32 v81, v82, v72
	v_pk_mul_f32 v[72:73], v[76:77], v[80:81] op_sel_hi:[1,0]
	s_nop 0
	v_mul_f32_e32 v76, 0xbfb8aa3b, v73
	v_exp_f32_e32 v76, v76
	s_nop 0
	v_add_f32_e32 v76, 1.0, v76
	v_rcp_f32_e32 v76, v76
	s_nop 0
	v_mul_f32_e32 v73, v73, v76
	v_mul_f32_e32 v76, v72, v73
	v_mov_b32_e32 v72, v74
	v_mov_b32_e32 v73, v78
	v_pk_mul_f32 v[72:73], v[72:73], v[80:81] op_sel_hi:[1,0]
	v_mov_b32_e32 v78, v75
	v_mul_f32_e32 v74, 0xbfb8aa3b, v73
	v_exp_f32_e32 v74, v74
	s_nop 0
	v_add_f32_e32 v74, 1.0, v74
	v_rcp_f32_e32 v74, v74
	s_nop 0
	v_mul_f32_e32 v73, v73, v74
	v_mul_f32_e32 v74, v72, v73
	v_pk_mul_f32 v[72:73], v[78:79], v[80:81] op_sel_hi:[1,0]
	s_nop 0
	v_mul_f32_e32 v75, 0xbfb8aa3b, v73
	v_exp_f32_e32 v75, v75
	s_nop 0
	v_add_f32_e32 v75, 1.0, v75
	v_rcp_f32_e32 v75, v75
	s_nop 0
	v_mul_f32_e32 v73, v73, v75
	v_mul_f32_e32 v75, v72, v73
	v_mov_b32_e32 v72, v64
	v_mov_b32_e32 v73, v68
	v_pk_mul_f32 v[72:73], v[72:73], v[80:81] op_sel_hi:[1,0]
	v_mov_b32_e32 v68, v65
	v_mul_f32_e32 v64, 0xbfb8aa3b, v73
	v_exp_f32_e32 v64, v64
	s_nop 0
	v_add_f32_e32 v64, 1.0, v64
	v_rcp_f32_e32 v64, v64
	s_nop 0
	v_mul_f32_e32 v64, v73, v64
	v_mul_f32_e32 v72, v72, v64
	v_pk_mul_f32 v[64:65], v[68:69], v[80:81] op_sel_hi:[1,0]
	s_nop 0
	v_mul_f32_e32 v68, 0xbfb8aa3b, v65
	v_exp_f32_e32 v68, v68
	s_nop 0
	v_add_f32_e32 v68, 1.0, v68
	v_rcp_f32_e32 v68, v68
	s_nop 0
	v_mul_f32_e32 v65, v65, v68
	v_mul_f32_e32 v68, v64, v65
	v_mov_b32_e32 v64, v66
	v_mov_b32_e32 v65, v70
	v_pk_mul_f32 v[64:65], v[64:65], v[80:81] op_sel_hi:[1,0]
	v_mov_b32_e32 v70, v67
	v_mul_f32_e32 v66, 0xbfb8aa3b, v65
	v_exp_f32_e32 v66, v66
	s_nop 0
	v_add_f32_e32 v66, 1.0, v66
	v_rcp_f32_e32 v66, v66
	s_nop 0
	v_mul_f32_e32 v65, v65, v66
	v_mul_f32_e32 v69, v64, v65
	v_pk_mul_f32 v[64:65], v[70:71], v[80:81] op_sel_hi:[1,0]
	s_nop 0
	v_mul_f32_e32 v66, 0xbfb8aa3b, v65
	v_exp_f32_e32 v66, v66
	s_nop 0
	v_add_f32_e32 v66, 1.0, v66
	v_rcp_f32_e32 v66, v66
	s_nop 0
	v_mul_f32_e32 v65, v65, v66
	v_mul_f32_e32 v67, v64, v65
	v_cvt_pk_bf16_f32 v64, v81, v76
	v_cvt_pk_bf16_f32 v65, v74, v75
	v_cvt_pk_bf16_f32 v66, v72, v68
	v_add_co_u32_e32 v68, vcc, s20, v112
	v_cvt_pk_bf16_f32 v67, v69, v67
	s_mov_b32 s20, 0x160000
	s_nop 0
	v_addc_co_u32_e32 v69, vcc, 0, v113, vcc
	global_store_dwordx4 v[68:69], v[64:67], off
	s_cmp_eq_u32 s57, 6
	s_cbranch_scc0 .Lp7_blk4
	s_cmp_eq_u32 s10, 0x100
	s_cbranch_scc1 .Lp7_h0_skip
